# VM2 attention loops: the 8 next-step K-fragment LDS reads spread one per PV gap (gaps 1-8) instead of two per gap in gaps 3-6 (no gap with 2 tr + 2 b128 reads); on top of v18
# speedup vs baseline: 1.0109x; 1.0109x over previous
.LBB0_863:
	v_mfma_f32_32x32x16_bf16 v[112:127], v[100:103], v[218:221], 0
	v_lshl_add_u32 v206, s89, 1, v168
	ds_read_b64_tr_b16 v[194:195], v206 offset:24576
	ds_read_b64_tr_b16 v[196:197], v206 offset:25088
	v_add_f32_e32 v108, v80, v81
	v_add_f32_e32 v108, v82, v108
	v_add_f32_e32 v108, v83, v108
	v_add_f32_e32 v108, v84, v108
	v_add_f32_e32 v108, v85, v108
	v_cvt_pk_bf16_f32 v156, v80, v81
	v_cvt_pk_bf16_f32 v157, v82, v83
	ds_read_b64_tr_b16 v[80:81], v206 offset:28672
	ds_read_b64_tr_b16 v[82:83], v206 offset:29184
	v_add_f32_e32 v104, v86, v108
	v_add_f32_e32 v104, v87, v104
	v_add_f32_e32 v104, v88, v104
	v_add_f32_e32 v144, v89, v104
	v_mfma_f32_32x32x16_bf16 v[96:111], v[96:99], v[218:221], 0
	v_cvt_pk_bf16_f32 v158, v84, v85
	v_cvt_pk_bf16_f32 v159, v86, v87
	ds_read_b64_tr_b16 v[84:85], v206 offset:25600
	ds_read_b64_tr_b16 v[86:87], v206 offset:26112
	v_add_f32_e32 v144, v90, v144
	v_add_f32_e32 v144, v91, v144
	v_add_f32_e32 v144, v92, v144
	v_add_f32_e32 v144, v93, v144
	v_cvt_pk_bf16_f32 v152, v88, v89
	v_cvt_pk_bf16_f32 v153, v90, v91
	v_mfma_f32_32x32x16_bf16 v[112:127], v[164:167], v[222:225], v[112:127]
	ds_read_b64_tr_b16 v[88:89], v206 offset:29696
	ds_read_b64_tr_b16 v[90:91], v206 offset:30208
	v_add_f32_e32 v144, v94, v144
	v_add_f32_e32 v144, v95, v144
	v_add_f32_e32 v144, v64, v144
	v_add_f32_e32 v144, v65, v144
	v_mfma_f32_32x32x16_bf16 v[96:111], v[160:163], v[222:225], v[96:111]
	v_cvt_pk_bf16_f32 v154, v92, v93
	v_cvt_pk_bf16_f32 v155, v94, v95
	ds_read_b64_tr_b16 v[92:93], v206 offset:26624
	ds_read_b64_tr_b16 v[94:95], v206 offset:27136
	v_add_f32_e32 v144, v66, v144
	v_add_f32_e32 v144, v67, v144
	v_add_f32_e32 v144, v68, v144
	v_add_f32_e32 v144, v69, v144
	v_cvt_pk_bf16_f32 v148, v64, v65
	v_cvt_pk_bf16_f32 v149, v66, v67
	v_mfma_f32_32x32x16_bf16 v[112:127], v[140:143], v[226:229], v[112:127]
	ds_read_b64_tr_b16 v[198:199], v206 offset:30720
	ds_read_b64_tr_b16 v[200:201], v206 offset:31232
	v_add_f32_e32 v140, v70, v144
	v_add_f32_e32 v140, v71, v140
	v_add_f32_e32 v140, v72, v140
	v_add_f32_e32 v140, v73, v140
	v_mfma_f32_32x32x16_bf16 v[96:111], v[136:139], v[226:229], v[96:111]
	v_cvt_pk_bf16_f32 v150, v68, v69
	v_cvt_pk_bf16_f32 v151, v70, v71
	ds_read_b64_tr_b16 v[202:203], v206 offset:27648
	ds_read_b64_tr_b16 v[204:205], v206 offset:28160
	v_add_f32_e32 v68, v74, v140
	v_add_f32_e32 v68, v75, v68
	v_add_f32_e32 v68, v76, v68
	v_add_f32_e32 v68, v77, v68
	v_cvt_pk_bf16_f32 v144, v72, v73
	v_cvt_pk_bf16_f32 v145, v74, v75
	v_mfma_f32_32x32x16_bf16 v[112:127], v[132:135], v[230:233], v[112:127]
	ds_read_b64_tr_b16 v[72:73], v206 offset:31744
	ds_read_b64_tr_b16 v[74:75], v206 offset:32256
	v_add_f32_e32 v68, v78, v68
	v_add_f32_e32 v68, v79, v68
	v_add_f32_e32 v68, 0, v68
	v_cvt_pk_bf16_f32 v146, v76, v77
	v_mfma_f32_32x32x16_bf16 v[96:111], v[128:131], v[230:233], v[96:111]
	v_cvt_pk_bf16_f32 v147, v78, v79
	s_add_i32 s88, s87, s35
	v_lshl_add_u64 v[64:65], v[180:181], 0, s[54:55]
	s_mov_b32 s89, m0
	s_mov_b32 m0, s88
	s_nop 0
	global_load_lds_dwordx4 v[64:65], off
	s_mov_b32 m0, s89
	s_lshl_b32 s88, s86, 1
	v_lshl_add_u64 v[64:65], v[178:179], 0, s[54:55]
	s_add_i32 s88, s88, s16
	s_mov_b32 s89, m0
	s_mov_b32 m0, s88
	s_nop 0
	global_load_lds_dwordx4 v[64:65], off
	s_mov_b32 m0, s89
	v_lshl_add_u64 v[64:65], v[176:177], 0, s[54:55]
	s_addk_i32 s88, 0x2000
	s_mov_b32 s89, m0
	s_mov_b32 m0, s88
	s_nop 0
	global_load_lds_dwordx4 v[64:65], off
	s_mov_b32 m0, s89
	v_add_f32_e32 v193, v193, v68
	v_add_u32_e32 v242, s86, v234
	v_add_u32_e32 v243, s86, v235
	v_add_u32_e32 v244, s86, v236
	v_add_u32_e32 v245, s86, v237
	s_waitcnt lgkmcnt(12)
	v_mfma_f32_32x32x16_bf16 v[48:63], v[156:159], v[194:197], v[48:63]
	ds_read_b64_tr_b16 v[76:77], v206 offset:32768
	ds_read_b64_tr_b16 v[78:79], v206 offset:33280
	v_exp_f32_e32 v112, v112
	v_exp_f32_e32 v113, v113
	ds_read_b128 v[68:71], v242
	v_mfma_f32_32x32x16_bf16 v[32:47], v[156:159], v[80:83], v[32:47]
	ds_read_b64_tr_b16 v[194:195], v206 offset:36864
	ds_read_b64_tr_b16 v[196:197], v206 offset:37376
	v_exp_f32_e32 v114, v114
	v_exp_f32_e32 v115, v115
	ds_read_b128 v[64:67], v242 offset:4096
	s_waitcnt lgkmcnt(14)
	v_mfma_f32_32x32x16_bf16 v[48:63], v[152:155], v[84:87], v[48:63]
	ds_read_b64_tr_b16 v[80:81], v206 offset:33792
	ds_read_b64_tr_b16 v[82:83], v206 offset:34304
	v_exp_f32_e32 v116, v116
	v_exp_f32_e32 v117, v117
	ds_read_b128 v[164:167], v243
	v_mfma_f32_32x32x16_bf16 v[32:47], v[152:155], v[88:91], v[32:47]
	ds_read_b64_tr_b16 v[84:85], v206 offset:37888
	ds_read_b64_tr_b16 v[86:87], v206 offset:38400
	v_exp_f32_e32 v118, v118
	v_exp_f32_e32 v119, v119
	ds_read_b128 v[140:143], v243 offset:4096
	s_waitcnt lgkmcnt(14)
	v_mfma_f32_32x32x16_bf16 v[48:63], v[148:151], v[92:95], v[48:63]
	ds_read_b64_tr_b16 v[88:89], v206 offset:34816
	ds_read_b64_tr_b16 v[90:91], v206 offset:35328
	v_exp_f32_e32 v120, v120
	v_exp_f32_e32 v121, v121
	ds_read_b128 v[160:163], v244
	v_mfma_f32_32x32x16_bf16 v[32:47], v[148:151], v[198:201], v[32:47]
	ds_read_b64_tr_b16 v[92:93], v206 offset:38912
	ds_read_b64_tr_b16 v[94:95], v206 offset:39424
	v_exp_f32_e32 v122, v122
	v_exp_f32_e32 v123, v123
	ds_read_b128 v[132:135], v244 offset:4096
	s_waitcnt lgkmcnt(14)
	v_mfma_f32_32x32x16_bf16 v[48:63], v[144:147], v[202:205], v[48:63]
	ds_read_b64_tr_b16 v[198:199], v206 offset:35840
	ds_read_b64_tr_b16 v[200:201], v206 offset:36352
	v_exp_f32_e32 v124, v124
	v_exp_f32_e32 v125, v125
	ds_read_b128 v[136:139], v245
	v_mfma_f32_32x32x16_bf16 v[32:47], v[144:147], v[72:75], v[32:47]
	ds_read_b64_tr_b16 v[202:203], v206 offset:39936
	ds_read_b64_tr_b16 v[204:205], v206 offset:40448
	v_exp_f32_e32 v126, v126
	v_exp_f32_e32 v127, v127
	ds_read_b128 v[128:131], v245 offset:4096
	s_waitcnt lgkmcnt(14)
	v_mfma_f32_32x32x16_bf16 v[16:31], v[156:159], v[76:79], v[16:31]
	v_exp_f32_e32 v96, v96
	v_exp_f32_e32 v97, v97
	v_mfma_f32_32x32x16_bf16 v[0:15], v[156:159], v[194:197], v[0:15]
	v_exp_f32_e32 v98, v98
	v_exp_f32_e32 v99, v99
	v_mfma_f32_32x32x16_bf16 v[16:31], v[152:155], v[80:83], v[16:31]
	v_exp_f32_e32 v100, v100
	v_exp_f32_e32 v101, v101
	s_waitcnt lgkmcnt(12)
	v_mfma_f32_32x32x16_bf16 v[0:15], v[152:155], v[84:87], v[0:15]
	v_exp_f32_e32 v102, v102
	v_exp_f32_e32 v103, v103
	s_waitcnt lgkmcnt(8)
	v_mfma_f32_32x32x16_bf16 v[16:31], v[148:151], v[88:91], v[16:31]
	v_exp_f32_e32 v104, v104
	v_exp_f32_e32 v105, v105
	s_waitcnt lgkmcnt(4)
	v_mfma_f32_32x32x16_bf16 v[0:15], v[148:151], v[92:95], v[0:15]
	v_exp_f32_e32 v106, v106
	v_exp_f32_e32 v107, v107
	s_waitcnt lgkmcnt(2)
	v_mfma_f32_32x32x16_bf16 v[16:31], v[144:147], v[198:201], v[16:31]
	v_exp_f32_e32 v108, v108
	v_exp_f32_e32 v109, v109
	s_waitcnt lgkmcnt(0)
	v_mfma_f32_32x32x16_bf16 v[0:15], v[144:147], v[202:205], v[0:15]
	v_exp_f32_e32 v110, v110
	v_exp_f32_e32 v111, v111
	s_waitcnt vmcnt(3) lgkmcnt(0)
	s_barrier
	v_mfma_f32_32x32x16_bf16 v[80:95], v[68:71], v[218:221], 0
	s_add_i32 s88, s86, 0x2000
	s_cmpk_lg_i32 s86, 0x4000
	s_cselect_b32 s88, s88, 0
	v_lshl_add_u32 v206, s87, 1, v168
	ds_read_b64_tr_b16 v[194:195], v206 offset:24576
	ds_read_b64_tr_b16 v[196:197], v206 offset:25088
	v_add_f32_e32 v76, v112, v113
	v_add_f32_e32 v76, v114, v76
	v_add_f32_e32 v76, v115, v76
	v_add_f32_e32 v76, v116, v76
	v_add_f32_e32 v76, v117, v76
	v_cvt_pk_bf16_f32 v156, v112, v113
	v_cvt_pk_bf16_f32 v157, v114, v115
	ds_read_b64_tr_b16 v[112:113], v206 offset:28672
	ds_read_b64_tr_b16 v[114:115], v206 offset:29184
	v_add_f32_e32 v72, v118, v76
	v_add_f32_e32 v72, v119, v72
	v_add_f32_e32 v72, v120, v72
	v_add_f32_e32 v144, v121, v72
	v_mfma_f32_32x32x16_bf16 v[64:79], v[64:67], v[218:221], 0
	v_cvt_pk_bf16_f32 v158, v116, v117
	v_cvt_pk_bf16_f32 v159, v118, v119
	ds_read_b64_tr_b16 v[116:117], v206 offset:25600
	ds_read_b64_tr_b16 v[118:119], v206 offset:26112
	v_add_f32_e32 v144, v122, v144
	v_add_f32_e32 v144, v123, v144
	v_add_f32_e32 v144, v124, v144
	v_add_f32_e32 v144, v125, v144
	v_mfma_f32_32x32x16_bf16 v[80:95], v[164:167], v[222:225], v[80:95]
	v_cvt_pk_bf16_f32 v152, v120, v121
	v_cvt_pk_bf16_f32 v153, v122, v123
	ds_read_b64_tr_b16 v[120:121], v206 offset:29696
	ds_read_b64_tr_b16 v[122:123], v206 offset:30208
	v_add_f32_e32 v144, v126, v144
	v_add_f32_e32 v144, v127, v144
	v_add_f32_e32 v144, v96, v144
	v_add_f32_e32 v144, v97, v144
	v_mfma_f32_32x32x16_bf16 v[64:79], v[140:143], v[222:225], v[64:79]
	v_cvt_pk_bf16_f32 v154, v124, v125
	v_cvt_pk_bf16_f32 v155, v126, v127
	ds_read_b64_tr_b16 v[124:125], v206 offset:26624
	ds_read_b64_tr_b16 v[126:127], v206 offset:27136
	v_add_f32_e32 v144, v98, v144
	v_add_f32_e32 v144, v99, v144
	v_add_f32_e32 v144, v100, v144
	v_add_f32_e32 v144, v101, v144
	v_mfma_f32_32x32x16_bf16 v[80:95], v[160:163], v[226:229], v[80:95]
	v_cvt_pk_bf16_f32 v148, v96, v97
	v_cvt_pk_bf16_f32 v149, v98, v99
	ds_read_b64_tr_b16 v[198:199], v206 offset:30720
	ds_read_b64_tr_b16 v[200:201], v206 offset:31232
	v_add_f32_e32 v140, v102, v144
	v_add_f32_e32 v140, v103, v140
	v_add_f32_e32 v140, v104, v140
	v_add_f32_e32 v140, v105, v140
	v_mfma_f32_32x32x16_bf16 v[64:79], v[132:135], v[226:229], v[64:79]
	v_cvt_pk_bf16_f32 v150, v100, v101
	v_cvt_pk_bf16_f32 v151, v102, v103
	ds_read_b64_tr_b16 v[202:203], v206 offset:27648
	ds_read_b64_tr_b16 v[204:205], v206 offset:28160
	v_add_f32_e32 v100, v106, v140
	v_add_f32_e32 v100, v107, v100
	v_add_f32_e32 v100, v108, v100
	v_add_f32_e32 v100, v109, v100
	v_mfma_f32_32x32x16_bf16 v[80:95], v[136:139], v[230:233], v[80:95]
	v_cvt_pk_bf16_f32 v144, v104, v105
	v_cvt_pk_bf16_f32 v145, v106, v107
	ds_read_b64_tr_b16 v[104:105], v206 offset:31744
	ds_read_b64_tr_b16 v[106:107], v206 offset:32256
	v_add_f32_e32 v100, v110, v100
	v_add_f32_e32 v100, v111, v100
	v_add_f32_e32 v100, 0, v100
	v_cvt_pk_bf16_f32 v146, v108, v109
	v_mfma_f32_32x32x16_bf16 v[64:79], v[128:131], v[230:233], v[64:79]
	v_cvt_pk_bf16_f32 v147, v110, v111
	s_add_i32 s87, s86, s35
	s_mov_b32 s89, m0
	s_mov_b32 m0, s87
	s_nop 0
	global_load_lds_dwordx4 v[180:181], off
	s_mov_b32 m0, s89
	s_lshl_b32 s87, s88, 1
	s_add_i32 s87, s87, s16
	s_mov_b32 s89, m0
	s_mov_b32 m0, s87
	s_nop 0
	global_load_lds_dwordx4 v[178:179], off
	s_mov_b32 m0, s89
	s_addk_i32 s87, 0x2000
	s_mov_b32 s89, m0
	s_mov_b32 m0, s87
	s_nop 0
	global_load_lds_dwordx4 v[176:177], off
	s_mov_b32 m0, s89
	v_add_f32_e32 v193, v193, v100
	v_add_u32_e32 v242, s88, v234
	v_add_u32_e32 v243, s88, v235
	v_add_u32_e32 v244, s88, v236
	v_add_u32_e32 v245, s88, v237
	s_waitcnt lgkmcnt(12)
	v_mfma_f32_32x32x16_bf16 v[48:63], v[156:159], v[194:197], v[48:63]
	ds_read_b64_tr_b16 v[108:109], v206 offset:32768
	ds_read_b64_tr_b16 v[110:111], v206 offset:33280
	v_exp_f32_e32 v80, v80
	v_exp_f32_e32 v81, v81
	ds_read_b128 v[100:103], v242
	v_mfma_f32_32x32x16_bf16 v[32:47], v[156:159], v[112:115], v[32:47]
	ds_read_b64_tr_b16 v[194:195], v206 offset:36864
	ds_read_b64_tr_b16 v[196:197], v206 offset:37376
	v_exp_f32_e32 v82, v82
	v_exp_f32_e32 v83, v83
	ds_read_b128 v[96:99], v242 offset:4096
	s_waitcnt lgkmcnt(14)
	v_mfma_f32_32x32x16_bf16 v[48:63], v[152:155], v[116:119], v[48:63]
	ds_read_b64_tr_b16 v[112:113], v206 offset:33792
	ds_read_b64_tr_b16 v[114:115], v206 offset:34304
	v_exp_f32_e32 v84, v84
	v_exp_f32_e32 v85, v85
	ds_read_b128 v[164:167], v243
	v_mfma_f32_32x32x16_bf16 v[32:47], v[152:155], v[120:123], v[32:47]
	ds_read_b64_tr_b16 v[116:117], v206 offset:37888
	ds_read_b64_tr_b16 v[118:119], v206 offset:38400
	v_exp_f32_e32 v86, v86
	v_exp_f32_e32 v87, v87
	ds_read_b128 v[160:163], v243 offset:4096
	s_waitcnt lgkmcnt(14)
	v_mfma_f32_32x32x16_bf16 v[48:63], v[148:151], v[124:127], v[48:63]
	ds_read_b64_tr_b16 v[120:121], v206 offset:34816
	ds_read_b64_tr_b16 v[122:123], v206 offset:35328
	v_exp_f32_e32 v88, v88
	v_exp_f32_e32 v89, v89
	ds_read_b128 v[140:143], v244
	v_mfma_f32_32x32x16_bf16 v[32:47], v[148:151], v[198:201], v[32:47]
	ds_read_b64_tr_b16 v[124:125], v206 offset:38912
	ds_read_b64_tr_b16 v[126:127], v206 offset:39424
	v_exp_f32_e32 v90, v90
	v_exp_f32_e32 v91, v91
	ds_read_b128 v[136:139], v244 offset:4096
	s_waitcnt lgkmcnt(14)
	v_mfma_f32_32x32x16_bf16 v[48:63], v[144:147], v[202:205], v[48:63]
	ds_read_b64_tr_b16 v[198:199], v206 offset:35840
	ds_read_b64_tr_b16 v[200:201], v206 offset:36352
	v_exp_f32_e32 v92, v92
	v_exp_f32_e32 v93, v93
	ds_read_b128 v[132:135], v245
	v_mfma_f32_32x32x16_bf16 v[32:47], v[144:147], v[104:107], v[32:47]
	ds_read_b64_tr_b16 v[202:203], v206 offset:39936
	ds_read_b64_tr_b16 v[204:205], v206 offset:40448
	v_exp_f32_e32 v94, v94
	v_exp_f32_e32 v95, v95
	ds_read_b128 v[128:131], v245 offset:4096
	s_waitcnt lgkmcnt(14)
	v_mfma_f32_32x32x16_bf16 v[16:31], v[156:159], v[108:111], v[16:31]
	v_exp_f32_e32 v64, v64
	v_exp_f32_e32 v65, v65
	v_mfma_f32_32x32x16_bf16 v[0:15], v[156:159], v[194:197], v[0:15]
	v_exp_f32_e32 v66, v66
	v_exp_f32_e32 v67, v67
	v_mfma_f32_32x32x16_bf16 v[16:31], v[152:155], v[112:115], v[16:31]
	v_exp_f32_e32 v68, v68
	v_exp_f32_e32 v69, v69
	s_waitcnt lgkmcnt(12)
	v_mfma_f32_32x32x16_bf16 v[0:15], v[152:155], v[116:119], v[0:15]
	v_exp_f32_e32 v70, v70
	v_exp_f32_e32 v71, v71
	s_waitcnt lgkmcnt(8)
	v_mfma_f32_32x32x16_bf16 v[16:31], v[148:151], v[120:123], v[16:31]
	v_exp_f32_e32 v72, v72
	v_exp_f32_e32 v73, v73
	s_waitcnt lgkmcnt(4)
	v_mfma_f32_32x32x16_bf16 v[0:15], v[148:151], v[124:127], v[0:15]
	v_exp_f32_e32 v74, v74
	v_exp_f32_e32 v75, v75
	s_waitcnt lgkmcnt(2)
	v_mfma_f32_32x32x16_bf16 v[16:31], v[144:147], v[198:201], v[16:31]
	v_exp_f32_e32 v76, v76
	v_exp_f32_e32 v77, v77
	s_waitcnt lgkmcnt(0)
	v_mfma_f32_32x32x16_bf16 v[0:15], v[144:147], v[202:205], v[0:15]
	v_exp_f32_e32 v78, v78
	v_exp_f32_e32 v79, v79
	s_add_i32 s90, s88, 0x2000
	s_waitcnt vmcnt(3) lgkmcnt(0)
	s_barrier
; #define WAIT_BAR(N) asm volatile("s_waitcnt vmcnt(" #N ") lgkmcnt(0)\n\ts_barrier":::"memory")
;   #define RESC() do{ if(!NOMAX&&resc){ asm volatile("s_waitcnt lgkmcnt(0)":::"memory"); \
;       _Pragma("unroll") for(int d_=0;d_<2*VM;++d_) _Pragma("unroll") for(int r=0;r<16;++r)o[d_][r]*=wsf[crow(r,hi)]; } }while(0)
;   #define ROT() do{sl_prev=sl_cur;sl_cur=sl_next;sl_next=(sl_next==(NSLOT-1)*SLOTB)?0:sl_next+SLOTB;}while(0)
;   #define ENDW(tt) do{ if((tt)+3<NT){ if constexpr(VM==2){WAIT_BAR(3);}else{WAIT_BAR(2);} } else if((tt)+2<NT){ if constexpr(VM==2){WAIT_BAR(2);}else{WAIT_BAR(1);} } else {WAIT_BAR(0);} }while(0)
; template<int THRL,int VM,bool NOMAX> __device__ __forceinline__ void attn_unit(const bf16*Qb,const bf16*__restrict__ Kh,const bf16*__restrict__ Vh,bf16*Ob,const int NT,const int sp,float*wscr,char*shm){
;     ...
;   for(;t+5<NT;t+=2){
;     STEP(pB0,pB1,pA0,pA1,t,true,true,true);     if constexpr(VM==2){WAIT_BAR(3);}else{WAIT_BAR(2);} RESC(); ROT();
;     STEP(pA0,pA1,pB0,pB1,t+1,true,true,true);   if constexpr(VM==2){WAIT_BAR(3);}else{WAIT_BAR(2);} RESC(); ROT();
;   }
;     ...
;   for(;t+1<NT;t+=2){
;     STEP(pB0,pB1,pA0,pA1,t,(t+3<NT),(t+1<NT),(t+1<NT));       ENDW(t);   RESC(); ROT();
;     STEP(pA0,pA1,pB0,pB1,t+1,(t+4<NT),(t+2<NT),(t+2<NT));     ENDW(t+1); RESC(); ROT();
	s_cmpk_lg_i32 s88, 0x4000
	s_mov_b32 s89, s86
	s_cselect_b32 s86, s90, 0
	s_add_i32 s85, s85, 2
	v_lshl_add_u64 v[176:177], v[176:177], 0, s[56:57]
	v_lshl_add_u64 v[178:179], v[178:179], 0, s[56:57]
	v_lshl_add_u64 v[180:181], v[180:181], 0, s[56:57]
	s_mov_b32 s87, s88
	s_cmpk_lt_u32 s85, 0x79
	s_cbranch_scc1 .LBB0_863
	s_and_b32 s34, s34, 0x3fffffc0
	s_lshl_b32 s34, s34, 2
	s_add_i32 s34, s34, 0
	s_add_i32 s34, s34, 0x12000
	s_cmp_lg_u32 0, -1
	s_cselect_b32 s85, 0, 0
	s_add_i32 s86, s85, 0x6000
	v_add_u32_e32 v104, s86, v191
	v_add3_u32 v176, v104, v190, v192
	v_add_u32_e32 v177, 0x6000, v168
	ds_read_b64_tr_b16 v[178:179], v168 offset:57344
	ds_read_b64_tr_b16 v[180:181], v168 offset:57856
	v_add_f32_e32 v108, v80, v81
	ds_read_b128 v[104:107], v188
	v_add_f32_e32 v108, v82, v108
	v_add_f32_e32 v108, v83, v108
	v_add_f32_e32 v108, v84, v108
	v_add_f32_e32 v108, v85, v108
	v_cvt_pk_bf16_f32 v156, v80, v81
	v_cvt_pk_bf16_f32 v157, v82, v83
	s_waitcnt lgkmcnt(0)
	v_mfma_f32_32x32x16_bf16 v[112:127], v[100:103], v[104:107], 0
	ds_read_b64_tr_b16 v[80:81], v168 offset:61440
	ds_read_b64_tr_b16 v[82:83], v168 offset:61952
	ds_read_b128 v[100:103], v188
	v_add_f32_e32 v104, v86, v108
	v_add_f32_e32 v104, v87, v104
	v_add_f32_e32 v104, v88, v104
	v_add_f32_e32 v144, v89, v104
	v_cvt_pk_bf16_f32 v158, v84, v85
	v_cvt_pk_bf16_f32 v159, v86, v87
	s_waitcnt lgkmcnt(0)
	v_mfma_f32_32x32x16_bf16 v[96:111], v[96:99], v[100:103], 0
	ds_read_b64_tr_b16 v[84:85], v168 offset:58368
	ds_read_b64_tr_b16 v[86:87], v168 offset:58880
	ds_read_b128 v[194:197], v188 offset:1024
	v_add_f32_e32 v144, v90, v144
	v_add_f32_e32 v144, v91, v144
	v_add_f32_e32 v144, v92, v144
	v_add_f32_e32 v144, v93, v144
	v_cvt_pk_bf16_f32 v152, v88, v89
	v_cvt_pk_bf16_f32 v153, v90, v91
	s_waitcnt lgkmcnt(0)
	v_mfma_f32_32x32x16_bf16 v[112:127], v[164:167], v[194:197], v[112:127]
	ds_read_b64_tr_b16 v[88:89], v168 offset:62464
	ds_read_b64_tr_b16 v[90:91], v168 offset:62976
	ds_read_b128 v[164:167], v188 offset:1024
	v_add_f32_e32 v144, v94, v144
	v_add_f32_e32 v144, v95, v144
	v_add_f32_e32 v144, v64, v144
	v_add_f32_e32 v144, v65, v144
	v_cvt_pk_bf16_f32 v154, v92, v93
	v_cvt_pk_bf16_f32 v155, v94, v95
	s_waitcnt lgkmcnt(0)
	v_mfma_f32_32x32x16_bf16 v[96:111], v[160:163], v[164:167], v[96:111]
	ds_read_b64_tr_b16 v[194:195], v168 offset:59392
	ds_read_b64_tr_b16 v[196:197], v168 offset:59904
	ds_read_b128 v[92:95], v188 offset:2048
	v_add_f32_e32 v144, v66, v144
	v_add_f32_e32 v144, v67, v144
	v_add_f32_e32 v144, v68, v144
	v_add_f32_e32 v144, v69, v144
	v_cvt_pk_bf16_f32 v148, v64, v65
	v_cvt_pk_bf16_f32 v149, v66, v67
	s_waitcnt lgkmcnt(0)
	v_mfma_f32_32x32x16_bf16 v[112:127], v[140:143], v[92:95], v[112:127]
	ds_read_b64_tr_b16 v[140:141], v168 offset:63488
	ds_read_b64_tr_b16 v[142:143], v168 offset:64000
	ds_read_b128 v[64:67], v188 offset:2048
	v_add_f32_e32 v92, v70, v144
	v_add_f32_e32 v92, v71, v92
	v_add_f32_e32 v92, v72, v92
	v_add_f32_e32 v92, v73, v92
	v_cvt_pk_bf16_f32 v150, v68, v69
	v_cvt_pk_bf16_f32 v151, v70, v71
	s_waitcnt lgkmcnt(0)
	v_mfma_f32_32x32x16_bf16 v[96:111], v[136:139], v[64:67], v[96:111]
	ds_read_b64_tr_b16 v[136:137], v168 offset:60416
	ds_read_b64_tr_b16 v[138:139], v168 offset:60928
	ds_read_b128 v[64:67], v188 offset:3072
	v_add_f32_e32 v68, v74, v92
	v_add_f32_e32 v68, v75, v68
	v_add_f32_e32 v68, v76, v68
	v_add_f32_e32 v68, v77, v68
	v_cvt_pk_bf16_f32 v144, v72, v73
	v_cvt_pk_bf16_f32 v145, v74, v75
	s_waitcnt lgkmcnt(0)
	v_mfma_f32_32x32x16_bf16 v[112:127], v[132:135], v[64:67], v[112:127]
	ds_read_b64_tr_b16 v[72:73], v168 offset:64512
	ds_read_b64_tr_b16 v[74:75], v168 offset:65024
	ds_read_b128 v[64:67], v188 offset:3072
	v_add_f32_e32 v68, v78, v68
	v_add_f32_e32 v68, v79, v68
	v_add_f32_e32 v68, 0, v68
	v_cvt_pk_bf16_f32 v146, v76, v77
	v_cvt_pk_bf16_f32 v147, v78, v79
	s_waitcnt lgkmcnt(0)
	v_mfma_f32_32x32x16_bf16 v[96:111], v[128:131], v[64:67], v[96:111]
	v_lshl_add_u64 v[64:65], v[174:175], 0, s[58:59]
	s_mov_b32 s86, m0
	s_mov_b32 m0, s35
	s_nop 0
	global_load_lds_dwordx4 v[64:65], off
	s_mov_b32 m0, s86
	s_add_i32 s85, s85, s17
	v_lshl_add_u64 v[64:65], v[170:171], 0, s[60:61]
	s_add_i32 s17, s85, 0xa000
	s_mov_b32 s35, m0
	s_mov_b32 m0, s17
	s_nop 0
	global_load_lds_dwordx4 v[64:65], off
	s_mov_b32 m0, s35
	v_lshl_add_u64 v[64:65], v[172:173], 0, s[60:61]
	s_add_i32 s35, s17, 0x2000
	s_mov_b32 s86, m0
	s_mov_b32 m0, s35
	s_nop 0
	global_load_lds_dwordx4 v[64:65], off
	s_mov_b32 m0, s86
	v_add_f32_e32 v198, v193, v68
	v_mfma_f32_32x32x16_bf16 v[48:63], v[156:159], v[178:181], v[48:63]
	ds_read_b64_tr_b16 v[76:77], v177 offset:40960
	ds_read_b64_tr_b16 v[78:79], v177 offset:41472
	v_exp_f32_e32 v112, v112
	v_exp_f32_e32 v113, v113
	v_mfma_f32_32x32x16_bf16 v[32:47], v[156:159], v[80:83], v[32:47]
	ds_read_b64_tr_b16 v[128:129], v177 offset:45056
	ds_read_b64_tr_b16 v[130:131], v177 offset:45568
	v_exp_f32_e32 v114, v114
	v_exp_f32_e32 v115, v115
	ds_read_b128 v[68:71], v234 offset:8192
	ds_read_b128 v[64:67], v234 offset:12288
	v_mfma_f32_32x32x16_bf16 v[48:63], v[152:155], v[84:87], v[48:63]
	ds_read_b64_tr_b16 v[132:133], v177 offset:41984
	ds_read_b64_tr_b16 v[134:135], v177 offset:42496
	v_exp_f32_e32 v116, v116
	v_exp_f32_e32 v117, v117
	ds_read_b128 v[164:167], v235 offset:8192
	ds_read_b128 v[92:95], v235 offset:12288
	v_mfma_f32_32x32x16_bf16 v[32:47], v[152:155], v[88:91], v[32:47]
	ds_read_b64_tr_b16 v[178:179], v177 offset:46080
	ds_read_b64_tr_b16 v[180:181], v177 offset:46592
	v_exp_f32_e32 v118, v118
	v_exp_f32_e32 v119, v119
	ds_read_b128 v[160:163], v236 offset:8192
	ds_read_b128 v[84:87], v236 offset:12288
	v_mfma_f32_32x32x16_bf16 v[48:63], v[148:151], v[194:197], v[48:63]
	ds_read_b64_tr_b16 v[190:191], v177 offset:43008
	ds_read_b64_tr_b16 v[192:193], v177 offset:43520
	v_exp_f32_e32 v120, v120
	v_exp_f32_e32 v121, v121
	ds_read_b128 v[88:91], v237 offset:8192
	ds_read_b128 v[80:83], v237 offset:12288
	v_mfma_f32_32x32x16_bf16 v[32:47], v[148:151], v[140:143], v[32:47]
	ds_read_b64_tr_b16 v[194:195], v177 offset:47104
	ds_read_b64_tr_b16 v[196:197], v177 offset:47616
	v_exp_f32_e32 v122, v122
	v_exp_f32_e32 v123, v123
	v_mfma_f32_32x32x16_bf16 v[48:63], v[144:147], v[136:139], v[48:63]
	ds_read_b64_tr_b16 v[140:141], v177 offset:44032
	ds_read_b64_tr_b16 v[142:143], v177 offset:44544
	v_exp_f32_e32 v124, v124
	v_exp_f32_e32 v125, v125
	v_mfma_f32_32x32x16_bf16 v[32:47], v[144:147], v[72:75], v[32:47]
	ds_read_b64_tr_b16 v[136:137], v177 offset:48128
	ds_read_b64_tr_b16 v[138:139], v177 offset:48640
	v_exp_f32_e32 v126, v126
	v_exp_f32_e32 v127, v127
	s_waitcnt lgkmcnt(14)
;   #define RESC() do{ if(!NOMAX&&resc){ asm volatile("s_waitcnt lgkmcnt(0)":::"memory"); \
;       _Pragma("unroll") for(int d_=0;d_<2*VM;++d_) _Pragma("unroll") for(int r=0;r<16;++r)o[d_][r]*=wsf[crow(r,hi)]; } }while(0)
;   #define ROT() do{sl_prev=sl_cur;sl_cur=sl_next;sl_next=(sl_next==(NSLOT-1)*SLOTB)?0:sl_next+SLOTB;}while(0)
;   #define ENDW(tt) do{ if((tt)+3<NT){ if constexpr(VM==2){WAIT_BAR(3);}else{WAIT_BAR(2);} } else if((tt)+2<NT){ if constexpr(VM==2){WAIT_BAR(2);}else{WAIT_BAR(1);} } else {WAIT_BAR(0);} }while(0)
; template<int THRL,int VM,bool NOMAX> __device__ __forceinline__ void attn_unit(const bf16*Qb,const bf16*__restrict__ Kh,const bf16*__restrict__ Vh,bf16*Ob,const int NT,const int sp,float*wscr,char*shm){
;     ...
;   for(;t+1<NT;t+=2){
;     STEP(pB0,pB1,pA0,pA1,t,(t+3<NT),(t+1<NT),(t+1<NT));       ENDW(t);   RESC(); ROT();
;     STEP(pA0,pA1,pB0,pB1,t+1,(t+4<NT),(t+2<NT),(t+2<NT));     ENDW(t+1); RESC(); ROT();
	v_mfma_f32_32x32x16_bf16 v[16:31], v[156:159], v[76:79], v[16:31]
	v_exp_f32_e32 v96, v96
	v_exp_f32_e32 v97, v97
	v_mfma_f32_32x32x16_bf16 v[0:15], v[156:159], v[128:131], v[0:15]
	v_exp_f32_e32 v98, v98
	v_exp_f32_e32 v99, v99
	v_mfma_f32_32x32x16_bf16 v[16:31], v[152:155], v[132:135], v[16:31]
	v_exp_f32_e32 v100, v100
	v_exp_f32_e32 v101, v101
	s_waitcnt lgkmcnt(12)
	v_mfma_f32_32x32x16_bf16 v[0:15], v[152:155], v[178:181], v[0:15]
	v_exp_f32_e32 v102, v102
	v_exp_f32_e32 v103, v103
	s_waitcnt lgkmcnt(8)
	v_mfma_f32_32x32x16_bf16 v[16:31], v[148:151], v[190:193], v[16:31]
	v_exp_f32_e32 v104, v104
	v_exp_f32_e32 v105, v105
	s_waitcnt lgkmcnt(4)
	v_mfma_f32_32x32x16_bf16 v[0:15], v[148:151], v[194:197], v[0:15]
	v_exp_f32_e32 v106, v106
	v_exp_f32_e32 v107, v107
	s_waitcnt lgkmcnt(2)
	v_mfma_f32_32x32x16_bf16 v[16:31], v[144:147], v[140:143], v[16:31]
	v_exp_f32_e32 v108, v108
	v_exp_f32_e32 v109, v109
	s_waitcnt lgkmcnt(0)
	v_mfma_f32_32x32x16_bf16 v[0:15], v[144:147], v[136:139], v[0:15]
	v_exp_f32_e32 v110, v110
	v_exp_f32_e32 v111, v111
	s_waitcnt vmcnt(3) lgkmcnt(0)
	s_barrier
	ds_read_b64_tr_b16 v[178:179], v168 offset:24576
	ds_read_b64_tr_b16 v[180:181], v168 offset:25088
	v_add_f32_e32 v76, v112, v113
	ds_read_b128 v[72:75], v188
	v_add_f32_e32 v76, v114, v76
	v_add_f32_e32 v76, v115, v76
	v_add_f32_e32 v76, v116, v76
	v_add_f32_e32 v76, v117, v76
	v_cvt_pk_bf16_f32 v156, v112, v113
	v_cvt_pk_bf16_f32 v157, v114, v115
	s_waitcnt lgkmcnt(0)
	v_mfma_f32_32x32x16_bf16 v[128:143], v[68:71], v[72:75], 0
	ds_read_b64_tr_b16 v[112:113], v168 offset:28672
	ds_read_b64_tr_b16 v[114:115], v168 offset:29184
	ds_read_b128 v[68:71], v188
	v_add_f32_e32 v72, v118, v76
	v_add_f32_e32 v72, v119, v72
	v_add_f32_e32 v72, v120, v72
	v_add_f32_e32 v144, v121, v72
	s_waitcnt lgkmcnt(0)
	v_mfma_f32_32x32x16_bf16 v[64:79], v[64:67], v[68:71], 0
	v_cvt_pk_bf16_f32 v158, v116, v117
	v_cvt_pk_bf16_f32 v159, v118, v119
	ds_read_b64_tr_b16 v[116:117], v168 offset:25600
	ds_read_b64_tr_b16 v[118:119], v168 offset:26112
	ds_read_b128 v[190:193], v188 offset:1024
	v_add_f32_e32 v144, v122, v144
	v_add_f32_e32 v144, v123, v144
	v_add_f32_e32 v144, v124, v144
	v_add_f32_e32 v144, v125, v144
	v_cvt_pk_bf16_f32 v152, v120, v121
	v_cvt_pk_bf16_f32 v153, v122, v123
	s_waitcnt lgkmcnt(0)
	v_mfma_f32_32x32x16_bf16 v[128:143], v[164:167], v[190:193], v[128:143]
	ds_read_b64_tr_b16 v[120:121], v168 offset:29696
	ds_read_b64_tr_b16 v[122:123], v168 offset:30208
	ds_read_b128 v[164:167], v188 offset:1024
	v_add_f32_e32 v144, v126, v144
	v_add_f32_e32 v144, v127, v144
	v_add_f32_e32 v144, v96, v144
	v_add_f32_e32 v144, v97, v144
	s_waitcnt lgkmcnt(0)
	v_mfma_f32_32x32x16_bf16 v[64:79], v[92:95], v[164:167], v[64:79]
	v_cvt_pk_bf16_f32 v154, v124, v125
	v_cvt_pk_bf16_f32 v155, v126, v127
	ds_read_b64_tr_b16 v[92:93], v168 offset:26624
	ds_read_b64_tr_b16 v[94:95], v168 offset:27136
	ds_read_b128 v[124:127], v188 offset:2048
	v_add_f32_e32 v144, v98, v144
	v_add_f32_e32 v144, v99, v144
	v_add_f32_e32 v144, v100, v144
	v_add_f32_e32 v144, v101, v144
	v_cvt_pk_bf16_f32 v148, v96, v97
	v_cvt_pk_bf16_f32 v149, v98, v99
	s_waitcnt lgkmcnt(0)
	v_mfma_f32_32x32x16_bf16 v[128:143], v[160:163], v[124:127], v[128:143]
	ds_read_b64_tr_b16 v[96:97], v168 offset:30720
	ds_read_b64_tr_b16 v[98:99], v168 offset:31232
	ds_read_b128 v[124:127], v188 offset:2048
	v_add_f32_e32 v144, v102, v144
	v_add_f32_e32 v144, v103, v144
	v_add_f32_e32 v144, v104, v144
	v_add_f32_e32 v144, v105, v144
	s_waitcnt lgkmcnt(0)
	v_mfma_f32_32x32x16_bf16 v[64:79], v[84:87], v[124:127], v[64:79]
	v_cvt_pk_bf16_f32 v150, v100, v101
	v_cvt_pk_bf16_f32 v151, v102, v103
	ds_read_b64_tr_b16 v[100:101], v168 offset:27648
	ds_read_b64_tr_b16 v[102:103], v168 offset:28160
	ds_read_b128 v[84:87], v188 offset:3072
	v_add_f32_e32 v124, v106, v144
	v_add_f32_e32 v124, v107, v124
	v_add_f32_e32 v124, v108, v124
	v_add_f32_e32 v124, v109, v124
	v_cvt_pk_bf16_f32 v144, v104, v105
	v_cvt_pk_bf16_f32 v145, v106, v107
	s_waitcnt lgkmcnt(0)
	v_mfma_f32_32x32x16_bf16 v[128:143], v[88:91], v[84:87], v[128:143]
	ds_read_b64_tr_b16 v[88:89], v168 offset:31744
	ds_read_b64_tr_b16 v[90:91], v168 offset:32256
	ds_read_b128 v[84:87], v188 offset:3072
	v_add_f32_e32 v104, v110, v124
	v_add_f32_e32 v104, v111, v104
	v_add_f32_e32 v104, 0, v104
	v_cvt_pk_bf16_f32 v146, v108, v109
	s_waitcnt lgkmcnt(0)
;   #define RESC() do{ if(!NOMAX&&resc){ asm volatile("s_waitcnt lgkmcnt(0)":::"memory"); \
;       _Pragma("unroll") for(int d_=0;d_<2*VM;++d_) _Pragma("unroll") for(int r=0;r<16;++r)o[d_][r]*=wsf[crow(r,hi)]; } }while(0)
;   #define ROT() do{sl_prev=sl_cur;sl_cur=sl_next;sl_next=(sl_next==(NSLOT-1)*SLOTB)?0:sl_next+SLOTB;}while(0)
;   #define ENDW(tt) do{ if((tt)+3<NT){ if constexpr(VM==2){WAIT_BAR(3);}else{WAIT_BAR(2);} } else if((tt)+2<NT){ if constexpr(VM==2){WAIT_BAR(2);}else{WAIT_BAR(1);} } else {WAIT_BAR(0);} }while(0)
; template<int THRL,int VM,bool NOMAX> __device__ __forceinline__ void attn_unit(const bf16*Qb,const bf16*__restrict__ Kh,const bf16*__restrict__ Vh,bf16*Ob,const int NT,const int sp,float*wscr,char*shm){
;     ...
;   for(;t+1<NT;t+=2){
;     STEP(pB0,pB1,pA0,pA1,t,(t+3<NT),(t+1<NT),(t+1<NT));       ENDW(t);   RESC(); ROT();
;     STEP(pA0,pA1,pB0,pB1,t+1,(t+4<NT),(t+2<NT),(t+2<NT));     ENDW(t+1); RESC(); ROT();
	v_mfma_f32_32x32x16_bf16 v[64:79], v[80:83], v[84:87], v[64:79]
	v_cvt_pk_bf16_f32 v147, v110, v111
	v_lshl_add_u64 v[80:81], v[174:175], 0, s[62:63]
	s_add_i32 s86, s85, 0x2000
	s_mov_b32 s87, m0
	s_mov_b32 m0, s86
	s_nop 0
	global_load_lds_dwordx4 v[80:81], off
	s_mov_b32 m0, s87
	v_lshl_add_u64 v[80:81], v[170:171], 0, s[64:65]
	s_add_i32 s86, s85, 0xe000
	s_mov_b32 s87, m0
	s_mov_b32 m0, s86
	s_nop 0
	global_load_lds_dwordx4 v[80:81], off
	s_mov_b32 m0, s87
	v_lshl_add_u64 v[80:81], v[172:173], 0, s[64:65]
	s_add_i32 s85, s85, 0x10000
	s_mov_b32 s86, m0
	s_mov_b32 m0, s85
	s_nop 0
	global_load_lds_dwordx4 v[80:81], off
	s_mov_b32 m0, s86
	v_add_f32_e32 v198, v198, v104
	v_mfma_f32_32x32x16_bf16 v[48:63], v[156:159], v[178:181], v[48:63]
	ds_read_b64_tr_b16 v[104:105], v168 offset:32768
	ds_read_b64_tr_b16 v[106:107], v168 offset:33280
	v_exp_f32_e32 v128, v128
	v_exp_f32_e32 v129, v129
	v_mfma_f32_32x32x16_bf16 v[32:47], v[156:159], v[112:115], v[32:47]
	ds_read_b64_tr_b16 v[108:109], v168 offset:36864
	ds_read_b64_tr_b16 v[110:111], v168 offset:37376
	v_exp_f32_e32 v130, v130
	v_exp_f32_e32 v131, v131
	ds_read_b128 v[84:87], v234 offset:16384
	ds_read_b128 v[80:83], v234 offset:20480
	v_mfma_f32_32x32x16_bf16 v[48:63], v[152:155], v[116:119], v[48:63]
	ds_read_b64_tr_b16 v[178:179], v168 offset:33792
	ds_read_b64_tr_b16 v[180:181], v168 offset:34304
	v_exp_f32_e32 v132, v132
	v_exp_f32_e32 v133, v133
	ds_read_b128 v[164:167], v235 offset:16384
	ds_read_b128 v[124:127], v235 offset:20480
	v_mfma_f32_32x32x16_bf16 v[32:47], v[152:155], v[120:123], v[32:47]
	ds_read_b64_tr_b16 v[190:191], v168 offset:37888
	ds_read_b64_tr_b16 v[192:193], v168 offset:38400
	v_exp_f32_e32 v134, v134
	v_exp_f32_e32 v135, v135
	ds_read_b128 v[160:163], v236 offset:16384
	ds_read_b128 v[116:119], v236 offset:20480
	v_mfma_f32_32x32x16_bf16 v[48:63], v[148:151], v[92:95], v[48:63]
	ds_read_b64_tr_b16 v[194:195], v168 offset:34816
	ds_read_b64_tr_b16 v[196:197], v168 offset:35328
	v_exp_f32_e32 v136, v136
	v_exp_f32_e32 v137, v137
	ds_read_b128 v[120:123], v237 offset:16384
	ds_read_b128 v[112:115], v237 offset:20480
	v_mfma_f32_32x32x16_bf16 v[32:47], v[148:151], v[96:99], v[32:47]
	ds_read_b64_tr_b16 v[92:93], v168 offset:38912
	ds_read_b64_tr_b16 v[94:95], v168 offset:39424
	v_exp_f32_e32 v138, v138
	v_exp_f32_e32 v139, v139
	v_mfma_f32_32x32x16_bf16 v[48:63], v[144:147], v[100:103], v[48:63]
	ds_read_b64_tr_b16 v[96:97], v168 offset:35840
	ds_read_b64_tr_b16 v[98:99], v168 offset:36352
	v_exp_f32_e32 v140, v140
	v_exp_f32_e32 v141, v141
	v_mfma_f32_32x32x16_bf16 v[32:47], v[144:147], v[88:91], v[32:47]
	ds_read_b64_tr_b16 v[100:101], v168 offset:39936
	ds_read_b64_tr_b16 v[102:103], v168 offset:40448
	v_exp_f32_e32 v142, v142
	v_exp_f32_e32 v143, v143
	s_waitcnt lgkmcnt(14)
	v_mfma_f32_32x32x16_bf16 v[16:31], v[156:159], v[104:107], v[16:31]
	v_exp_f32_e32 v64, v64
	v_exp_f32_e32 v65, v65
	v_mfma_f32_32x32x16_bf16 v[0:15], v[156:159], v[108:111], v[0:15]
	v_exp_f32_e32 v66, v66
	v_exp_f32_e32 v67, v67
	v_mfma_f32_32x32x16_bf16 v[16:31], v[152:155], v[178:181], v[16:31]
	v_exp_f32_e32 v68, v68
	v_exp_f32_e32 v69, v69
	s_waitcnt lgkmcnt(12)
	v_mfma_f32_32x32x16_bf16 v[0:15], v[152:155], v[190:193], v[0:15]
	v_exp_f32_e32 v70, v70
	v_exp_f32_e32 v71, v71
	s_waitcnt lgkmcnt(8)
	v_mfma_f32_32x32x16_bf16 v[16:31], v[148:151], v[194:197], v[16:31]
	v_exp_f32_e32 v72, v72
	v_exp_f32_e32 v73, v73
	s_waitcnt lgkmcnt(4)
	v_mfma_f32_32x32x16_bf16 v[0:15], v[148:151], v[92:95], v[0:15]
	v_exp_f32_e32 v74, v74
	v_exp_f32_e32 v75, v75
	s_waitcnt lgkmcnt(2)
	v_mfma_f32_32x32x16_bf16 v[16:31], v[144:147], v[96:99], v[16:31]
	v_exp_f32_e32 v76, v76
	v_exp_f32_e32 v77, v77
	s_waitcnt lgkmcnt(0)
	v_mfma_f32_32x32x16_bf16 v[0:15], v[144:147], v[100:103], v[0:15]
	v_exp_f32_e32 v78, v78
	v_exp_f32_e32 v79, v79
	s_waitcnt vmcnt(3) lgkmcnt(0)
	s_barrier
	ds_read_b64_tr_b16 v[178:179], v168 offset:40960
	ds_read_b64_tr_b16 v[180:181], v168 offset:41472
	v_add_f32_e32 v92, v128, v129
	ds_read_b128 v[88:91], v188
	v_add_f32_e32 v92, v130, v92
	v_add_f32_e32 v92, v131, v92
	v_add_f32_e32 v92, v132, v92
	v_add_f32_e32 v92, v133, v92
	v_cvt_pk_bf16_f32 v156, v128, v129
	v_cvt_pk_bf16_f32 v157, v130, v131
	s_waitcnt lgkmcnt(0)
	v_mfma_f32_32x32x16_bf16 v[96:111], v[84:87], v[88:91], 0
	ds_read_b64_tr_b16 v[128:129], v168 offset:45056
	ds_read_b64_tr_b16 v[130:131], v168 offset:45568
	ds_read_b128 v[84:87], v188
	v_add_f32_e32 v88, v134, v92
	v_add_f32_e32 v88, v135, v88
	v_add_f32_e32 v88, v136, v88
	v_add_f32_e32 v144, v137, v88
	v_cvt_pk_bf16_f32 v158, v132, v133
	v_cvt_pk_bf16_f32 v159, v134, v135
	s_waitcnt lgkmcnt(0)
	v_mfma_f32_32x32x16_bf16 v[80:95], v[80:83], v[84:87], 0
	ds_read_b64_tr_b16 v[132:133], v168 offset:41984
	ds_read_b64_tr_b16 v[134:135], v168 offset:42496
	ds_read_b128 v[190:193], v188 offset:1024
	v_add_f32_e32 v144, v138, v144
	v_add_f32_e32 v144, v139, v144
	v_add_f32_e32 v144, v140, v144
	v_add_f32_e32 v144, v141, v144
	v_cvt_pk_bf16_f32 v152, v136, v137
	v_cvt_pk_bf16_f32 v153, v138, v139
	s_waitcnt lgkmcnt(0)
	v_mfma_f32_32x32x16_bf16 v[96:111], v[164:167], v[190:193], v[96:111]
	ds_read_b64_tr_b16 v[136:137], v168 offset:46080
	ds_read_b64_tr_b16 v[138:139], v168 offset:46592
	ds_read_b128 v[164:167], v188 offset:1024
	v_add_f32_e32 v144, v142, v144
	v_add_f32_e32 v144, v143, v144
	v_add_f32_e32 v144, v64, v144
	v_add_f32_e32 v144, v65, v144
	v_cvt_pk_bf16_f32 v154, v140, v141
	v_cvt_pk_bf16_f32 v155, v142, v143
	s_waitcnt lgkmcnt(0)
;   #define RESC() do{ if(!NOMAX&&resc){ asm volatile("s_waitcnt lgkmcnt(0)":::"memory"); \
;       _Pragma("unroll") for(int d_=0;d_<2*VM;++d_) _Pragma("unroll") for(int r=0;r<16;++r)o[d_][r]*=wsf[crow(r,hi)]; } }while(0)
;   #define ROT() do{sl_prev=sl_cur;sl_cur=sl_next;sl_next=(sl_next==(NSLOT-1)*SLOTB)?0:sl_next+SLOTB;}while(0)
;   #define ENDW(tt) do{ if((tt)+3<NT){ if constexpr(VM==2){WAIT_BAR(3);}else{WAIT_BAR(2);} } else if((tt)+2<NT){ if constexpr(VM==2){WAIT_BAR(2);}else{WAIT_BAR(1);} } else {WAIT_BAR(0);} }while(0)
; template<int THRL,int VM,bool NOMAX> __device__ __forceinline__ void attn_unit(const bf16*Qb,const bf16*__restrict__ Kh,const bf16*__restrict__ Vh,bf16*Ob,const int NT,const int sp,float*wscr,char*shm){
;     ...
;   for(;t+1<NT;t+=2){
;     STEP(pB0,pB1,pA0,pA1,t,(t+3<NT),(t+1<NT),(t+1<NT));       ENDW(t);   RESC(); ROT();
;     STEP(pA0,pA1,pB0,pB1,t+1,(t+4<NT),(t+2<NT),(t+2<NT));     ENDW(t+1); RESC(); ROT();
	v_mfma_f32_32x32x16_bf16 v[80:95], v[124:127], v[164:167], v[80:95]
	ds_read_b64_tr_b16 v[124:125], v168 offset:43008
	ds_read_b64_tr_b16 v[126:127], v168 offset:43520
	ds_read_b128 v[140:143], v188 offset:2048
	v_add_f32_e32 v144, v66, v144
	v_add_f32_e32 v144, v67, v144
	v_add_f32_e32 v144, v68, v144
	v_add_f32_e32 v144, v69, v144
	v_cvt_pk_bf16_f32 v148, v64, v65
	v_cvt_pk_bf16_f32 v149, v66, v67
	s_waitcnt lgkmcnt(0)
	v_mfma_f32_32x32x16_bf16 v[96:111], v[160:163], v[140:143], v[96:111]
	ds_read_b64_tr_b16 v[190:191], v168 offset:47104
	ds_read_b64_tr_b16 v[192:193], v168 offset:47616
	ds_read_b128 v[64:67], v188 offset:2048
	v_add_f32_e32 v140, v70, v144
	v_add_f32_e32 v140, v71, v140
	v_add_f32_e32 v140, v72, v140
	v_add_f32_e32 v140, v73, v140
	v_cvt_pk_bf16_f32 v150, v68, v69
	v_cvt_pk_bf16_f32 v151, v70, v71
	s_waitcnt lgkmcnt(0)
	v_mfma_f32_32x32x16_bf16 v[80:95], v[116:119], v[64:67], v[80:95]
	ds_read_b64_tr_b16 v[116:117], v168 offset:44032
	ds_read_b64_tr_b16 v[118:119], v168 offset:44544
	ds_read_b128 v[64:67], v188 offset:3072
	v_add_f32_e32 v68, v74, v140
	v_add_f32_e32 v68, v75, v68
	v_add_f32_e32 v68, v76, v68
	v_add_f32_e32 v68, v77, v68
	v_cvt_pk_bf16_f32 v144, v72, v73
	v_cvt_pk_bf16_f32 v145, v74, v75
	s_waitcnt lgkmcnt(0)
	v_mfma_f32_32x32x16_bf16 v[96:111], v[120:123], v[64:67], v[96:111]
	ds_read_b64_tr_b16 v[72:73], v168 offset:48128
	ds_read_b64_tr_b16 v[74:75], v168 offset:48640
	ds_read_b128 v[64:67], v188 offset:3072
	v_add_f32_e32 v68, v78, v68
	v_add_f32_e32 v68, v79, v68
	v_add_f32_e32 v68, 0, v68
	v_cvt_pk_bf16_f32 v146, v76, v77
	v_cvt_pk_bf16_f32 v147, v78, v79
	s_waitcnt lgkmcnt(0)
	v_mfma_f32_32x32x16_bf16 v[80:95], v[112:115], v[64:67], v[80:95]
	v_lshl_add_u64 v[64:65], v[170:171], 0, s[58:59]
	s_mov_b32 s85, m0
	s_mov_b32 m0, s16
	s_nop 0
	global_load_lds_dwordx4 v[64:65], off
	s_mov_b32 m0, s85
	v_lshl_add_u64 v[64:65], v[172:173], 0, s[58:59]
	s_addk_i32 s16, 0x2000
	s_mov_b32 s85, m0
	s_mov_b32 m0, s16
	s_nop 0
	global_load_lds_dwordx4 v[64:65], off
	s_mov_b32 m0, s85
	v_add_f32_e32 v174, v198, v68
	v_mfma_f32_32x32x16_bf16 v[48:63], v[156:159], v[178:181], v[48:63]
	ds_read_b64_tr_b16 v[76:77], v168 offset:49152
	ds_read_b64_tr_b16 v[78:79], v168 offset:49664
	v_exp_f32_e32 v96, v96
	v_exp_f32_e32 v97, v97
	v_mfma_f32_32x32x16_bf16 v[32:47], v[156:159], v[128:131], v[32:47]
	ds_read_b64_tr_b16 v[112:113], v168 offset:53248
	ds_read_b64_tr_b16 v[114:115], v168 offset:53760
	v_exp_f32_e32 v98, v98
	v_exp_f32_e32 v99, v99
	ds_read_b128 v[68:71], v234
	ds_read_b128 v[64:67], v234 offset:4096
	v_mfma_f32_32x32x16_bf16 v[48:63], v[152:155], v[132:135], v[48:63]
	ds_read_b64_tr_b16 v[120:121], v168 offset:50176
	ds_read_b64_tr_b16 v[122:123], v168 offset:50688
	v_exp_f32_e32 v100, v100
	v_exp_f32_e32 v101, v101
	ds_read_b128 v[164:167], v235
	ds_read_b128 v[140:143], v235 offset:4096
	v_mfma_f32_32x32x16_bf16 v[32:47], v[152:155], v[136:139], v[32:47]
	ds_read_b64_tr_b16 v[178:179], v168 offset:54272
	ds_read_b64_tr_b16 v[180:181], v168 offset:54784
	v_exp_f32_e32 v102, v102
	v_exp_f32_e32 v103, v103
	ds_read_b128 v[160:163], v236
	ds_read_b128 v[132:135], v236 offset:4096
	v_mfma_f32_32x32x16_bf16 v[48:63], v[148:151], v[124:127], v[48:63]
	ds_read_b64_tr_b16 v[194:195], v168 offset:51200
	ds_read_b64_tr_b16 v[196:197], v168 offset:51712
	v_exp_f32_e32 v104, v104
	v_exp_f32_e32 v105, v105
	ds_read_b128 v[136:139], v237
	ds_read_b128 v[128:131], v237 offset:4096
	v_mfma_f32_32x32x16_bf16 v[32:47], v[148:151], v[190:193], v[32:47]
	ds_read_b64_tr_b16 v[124:125], v168 offset:55296
	ds_read_b64_tr_b16 v[126:127], v168 offset:55808
	v_exp_f32_e32 v106, v106
	v_exp_f32_e32 v107, v107
	v_mfma_f32_32x32x16_bf16 v[48:63], v[144:147], v[116:119], v[48:63]
	ds_read_b64_tr_b16 v[190:191], v168 offset:52224
	ds_read_b64_tr_b16 v[192:193], v168 offset:52736
	v_exp_f32_e32 v108, v108
	v_exp_f32_e32 v109, v109
	v_mfma_f32_32x32x16_bf16 v[32:47], v[144:147], v[72:75], v[32:47]
	ds_read_b64_tr_b16 v[116:117], v168 offset:56320
	ds_read_b64_tr_b16 v[118:119], v168 offset:56832
	v_exp_f32_e32 v110, v110
	v_exp_f32_e32 v111, v111
	s_waitcnt lgkmcnt(14)
	v_mfma_f32_32x32x16_bf16 v[16:31], v[156:159], v[76:79], v[16:31]
	v_exp_f32_e32 v80, v80
	v_exp_f32_e32 v81, v81
	v_mfma_f32_32x32x16_bf16 v[0:15], v[156:159], v[112:115], v[0:15]
	v_exp_f32_e32 v82, v82
	v_exp_f32_e32 v83, v83
	v_mfma_f32_32x32x16_bf16 v[16:31], v[152:155], v[120:123], v[16:31]
	v_exp_f32_e32 v84, v84
	v_exp_f32_e32 v85, v85
	s_waitcnt lgkmcnt(12)
	v_mfma_f32_32x32x16_bf16 v[0:15], v[152:155], v[178:181], v[0:15]
	v_exp_f32_e32 v86, v86
	v_exp_f32_e32 v87, v87
	s_waitcnt lgkmcnt(8)
	v_mfma_f32_32x32x16_bf16 v[16:31], v[148:151], v[194:197], v[16:31]
	v_exp_f32_e32 v88, v88
	v_exp_f32_e32 v89, v89
	s_waitcnt lgkmcnt(4)
	v_mfma_f32_32x32x16_bf16 v[0:15], v[148:151], v[124:127], v[0:15]
	v_exp_f32_e32 v90, v90
	v_exp_f32_e32 v91, v91
	s_waitcnt lgkmcnt(2)
	v_mfma_f32_32x32x16_bf16 v[16:31], v[144:147], v[190:193], v[16:31]
	v_exp_f32_e32 v92, v92
	v_exp_f32_e32 v93, v93
	s_waitcnt lgkmcnt(0)
	v_mfma_f32_32x32x16_bf16 v[0:15], v[144:147], v[116:119], v[0:15]
	v_exp_f32_e32 v94, v94
	v_exp_f32_e32 v95, v95
	s_waitcnt vmcnt(2) lgkmcnt(0)
	s_barrier
;   #define RESC() do{ if(!NOMAX&&resc){ asm volatile("s_waitcnt lgkmcnt(0)":::"memory"); \
;       _Pragma("unroll") for(int d_=0;d_<2*VM;++d_) _Pragma("unroll") for(int r=0;r<16;++r)o[d_][r]*=wsf[crow(r,hi)]; } }while(0)
;   #define ROT() do{sl_prev=sl_cur;sl_cur=sl_next;sl_next=(sl_next==(NSLOT-1)*SLOTB)?0:sl_next+SLOTB;}while(0)
;   #define ENDW(tt) do{ if((tt)+3<NT){ if constexpr(VM==2){WAIT_BAR(3);}else{WAIT_BAR(2);} } else if((tt)+2<NT){ if constexpr(VM==2){WAIT_BAR(2);}else{WAIT_BAR(1);} } else {WAIT_BAR(0);} }while(0)
; template<int THRL,int VM,bool NOMAX> __device__ __forceinline__ void attn_unit(const bf16*Qb,const bf16*__restrict__ Kh,const bf16*__restrict__ Vh,bf16*Ob,const int NT,const int sp,float*wscr,char*shm){
;     ...
;   for(;t+1<NT;t+=2){
;     STEP(pB0,pB1,pA0,pA1,t,(t+3<NT),(t+1<NT),(t+1<NT));       ENDW(t);   RESC(); ROT();
;     STEP(pA0,pA1,pB0,pB1,t+1,(t+4<NT),(t+2<NT),(t+2<NT));     ENDW(t+1); RESC(); ROT();
	ds_read_b64_tr_b16 v[178:179], v168 offset:57344
	ds_read_b64_tr_b16 v[180:181], v168 offset:57856
	v_add_f32_e32 v76, v96, v97
	ds_read_b128 v[72:75], v188
	v_add_f32_e32 v76, v98, v76
	v_add_f32_e32 v76, v99, v76
	v_add_f32_e32 v76, v100, v76
	v_add_f32_e32 v76, v101, v76
	v_cvt_pk_bf16_f32 v156, v96, v97
	v_cvt_pk_bf16_f32 v157, v98, v99
	s_waitcnt lgkmcnt(0)
	v_mfma_f32_32x32x16_bf16 v[112:127], v[68:71], v[72:75], 0
	ds_read_b64_tr_b16 v[96:97], v168 offset:61440
	ds_read_b64_tr_b16 v[98:99], v168 offset:61952
	ds_read_b128 v[68:71], v188
	v_add_f32_e32 v72, v102, v76
	v_add_f32_e32 v72, v103, v72
	v_add_f32_e32 v72, v104, v72
	v_add_f32_e32 v144, v105, v72
	s_waitcnt lgkmcnt(0)
	v_mfma_f32_32x32x16_bf16 v[64:79], v[64:67], v[68:71], 0
	v_cvt_pk_bf16_f32 v158, v100, v101
	v_cvt_pk_bf16_f32 v159, v102, v103
	ds_read_b64_tr_b16 v[100:101], v168 offset:58368
	ds_read_b64_tr_b16 v[102:103], v168 offset:58880
	ds_read_b128 v[190:193], v188 offset:1024
	v_add_f32_e32 v144, v106, v144
	v_add_f32_e32 v144, v107, v144
	v_add_f32_e32 v144, v108, v144
	v_add_f32_e32 v144, v109, v144
	v_cvt_pk_bf16_f32 v152, v104, v105
	v_cvt_pk_bf16_f32 v153, v106, v107
	s_waitcnt lgkmcnt(0)
	v_mfma_f32_32x32x16_bf16 v[112:127], v[164:167], v[190:193], v[112:127]
	ds_read_b64_tr_b16 v[104:105], v168 offset:62464
	ds_read_b64_tr_b16 v[106:107], v168 offset:62976
	ds_read_b128 v[164:167], v188 offset:1024
	v_add_f32_e32 v144, v110, v144
	v_add_f32_e32 v144, v111, v144
	v_add_f32_e32 v144, v80, v144
	v_add_f32_e32 v144, v81, v144
	s_waitcnt lgkmcnt(0)
	v_mfma_f32_32x32x16_bf16 v[64:79], v[140:143], v[164:167], v[64:79]
	v_cvt_pk_bf16_f32 v154, v108, v109
	v_cvt_pk_bf16_f32 v155, v110, v111
	ds_read_b64_tr_b16 v[108:109], v168 offset:59392
	ds_read_b64_tr_b16 v[110:111], v168 offset:59904
	ds_read_b128 v[140:143], v188 offset:2048
	v_add_f32_e32 v144, v82, v144
	v_add_f32_e32 v144, v83, v144
	v_add_f32_e32 v144, v84, v144
	v_add_f32_e32 v144, v85, v144
	v_cvt_pk_bf16_f32 v148, v80, v81
	v_cvt_pk_bf16_f32 v149, v82, v83
	s_waitcnt lgkmcnt(0)
	v_mfma_f32_32x32x16_bf16 v[112:127], v[160:163], v[140:143], v[112:127]
	ds_read_b64_tr_b16 v[190:191], v168 offset:63488
	ds_read_b64_tr_b16 v[192:193], v168 offset:64000
	ds_read_b128 v[80:83], v188 offset:2048
	v_add_f32_e32 v140, v86, v144
	v_add_f32_e32 v140, v87, v140
	v_add_f32_e32 v140, v88, v140
	v_add_f32_e32 v140, v89, v140
	s_waitcnt lgkmcnt(0)
	v_mfma_f32_32x32x16_bf16 v[64:79], v[132:135], v[80:83], v[64:79]
	v_cvt_pk_bf16_f32 v150, v84, v85
	v_cvt_pk_bf16_f32 v151, v86, v87
	ds_read_b64_tr_b16 v[84:85], v168 offset:60416
	ds_read_b64_tr_b16 v[86:87], v168 offset:60928
	ds_read_b128 v[80:83], v188 offset:3072
	v_add_f32_e32 v132, v90, v140
	v_add_f32_e32 v132, v91, v132
	v_add_f32_e32 v132, v92, v132
	v_add_f32_e32 v132, v93, v132
	v_cvt_pk_bf16_f32 v144, v88, v89
	v_cvt_pk_bf16_f32 v145, v90, v91
	s_waitcnt lgkmcnt(0)
	v_mfma_f32_32x32x16_bf16 v[112:127], v[136:139], v[80:83], v[112:127]
	ds_read_b64_tr_b16 v[88:89], v168 offset:64512
	ds_read_b64_tr_b16 v[90:91], v168 offset:65024
	ds_read_b128 v[80:83], v188 offset:3072
	v_add_f32_e32 v132, v94, v132
	v_add_f32_e32 v132, v95, v132
	v_add_f32_e32 v132, 0, v132
	v_cvt_pk_bf16_f32 v146, v92, v93
	s_waitcnt lgkmcnt(0)
	v_mfma_f32_32x32x16_bf16 v[64:79], v[128:131], v[80:83], v[64:79]
	v_cvt_pk_bf16_f32 v147, v94, v95
	v_lshl_add_u64 v[80:81], v[170:171], 0, s[62:63]
	s_mov_b32 s16, m0
	s_mov_b32 m0, s17
	s_nop 0
	global_load_lds_dwordx4 v[80:81], off
	s_mov_b32 m0, s16
	v_lshl_add_u64 v[80:81], v[172:173], 0, s[62:63]
	s_mov_b32 s16, m0
	s_mov_b32 m0, s35
	s_nop 0
	global_load_lds_dwordx4 v[80:81], off
	s_mov_b32 m0, s16
	v_add_f32_e32 v174, v174, v132
	v_mfma_f32_32x32x16_bf16 v[48:63], v[156:159], v[178:181], v[48:63]
	ds_read_b64_tr_b16 v[92:93], v177 offset:40960
	ds_read_b64_tr_b16 v[94:95], v177 offset:41472
	v_exp_f32_e32 v112, v112
	v_exp_f32_e32 v113, v113
	v_mfma_f32_32x32x16_bf16 v[32:47], v[156:159], v[96:99], v[32:47]
	ds_read_b64_tr_b16 v[170:171], v177 offset:45056
	ds_read_b64_tr_b16 v[172:173], v177 offset:45568
	v_exp_f32_e32 v114, v114
	v_exp_f32_e32 v115, v115
	ds_read_b128 v[80:83], v234 offset:8192
	ds_read_b128 v[96:99], v234 offset:12288
	v_mfma_f32_32x32x16_bf16 v[48:63], v[152:155], v[100:103], v[48:63]
	ds_read_b64_tr_b16 v[178:179], v177 offset:41984
	ds_read_b64_tr_b16 v[180:181], v177 offset:42496
	v_exp_f32_e32 v116, v116
	v_exp_f32_e32 v117, v117
	ds_read_b128 v[164:167], v235 offset:8192
	ds_read_b128 v[140:143], v235 offset:12288
	v_mfma_f32_32x32x16_bf16 v[32:47], v[152:155], v[104:107], v[32:47]
	ds_read_b64_tr_b16 v[100:101], v177 offset:46080
	ds_read_b64_tr_b16 v[102:103], v177 offset:46592
	v_exp_f32_e32 v118, v118
	v_exp_f32_e32 v119, v119
	ds_read_b128 v[160:163], v236 offset:8192
	ds_read_b128 v[132:135], v236 offset:12288
	v_mfma_f32_32x32x16_bf16 v[48:63], v[148:151], v[108:111], v[48:63]
	ds_read_b64_tr_b16 v[104:105], v177 offset:43008
	ds_read_b64_tr_b16 v[106:107], v177 offset:43520
	v_exp_f32_e32 v120, v120
	v_exp_f32_e32 v121, v121
	ds_read_b128 v[136:139], v237 offset:8192
	ds_read_b128 v[128:131], v237 offset:12288
	v_mfma_f32_32x32x16_bf16 v[32:47], v[148:151], v[190:193], v[32:47]
	ds_read_b64_tr_b16 v[108:109], v177 offset:47104
	ds_read_b64_tr_b16 v[110:111], v177 offset:47616
	v_exp_f32_e32 v122, v122
	v_exp_f32_e32 v123, v123
	v_mfma_f32_32x32x16_bf16 v[48:63], v[144:147], v[84:87], v[48:63]
	ds_read_b64_tr_b16 v[190:191], v177 offset:44032
	ds_read_b64_tr_b16 v[192:193], v177 offset:44544
	v_exp_f32_e32 v124, v124
	v_exp_f32_e32 v125, v125
	v_mfma_f32_32x32x16_bf16 v[32:47], v[144:147], v[88:91], v[32:47]
	ds_read_b64_tr_b16 v[84:85], v177 offset:48128
	ds_read_b64_tr_b16 v[86:87], v177 offset:48640
	v_exp_f32_e32 v126, v126
	v_exp_f32_e32 v127, v127
	s_waitcnt lgkmcnt(14)
	v_mfma_f32_32x32x16_bf16 v[16:31], v[156:159], v[92:95], v[16:31]
	v_exp_f32_e32 v64, v64
	v_exp_f32_e32 v65, v65
	v_mfma_f32_32x32x16_bf16 v[0:15], v[156:159], v[170:173], v[0:15]
	v_exp_f32_e32 v66, v66
	v_exp_f32_e32 v67, v67
	v_mfma_f32_32x32x16_bf16 v[16:31], v[152:155], v[178:181], v[16:31]
	v_exp_f32_e32 v68, v68
	v_exp_f32_e32 v69, v69
	s_waitcnt lgkmcnt(12)
	v_mfma_f32_32x32x16_bf16 v[0:15], v[152:155], v[100:103], v[0:15]
	v_exp_f32_e32 v70, v70
	v_exp_f32_e32 v71, v71
	s_waitcnt lgkmcnt(8)
	v_mfma_f32_32x32x16_bf16 v[16:31], v[148:151], v[104:107], v[16:31]
	v_exp_f32_e32 v72, v72
	v_exp_f32_e32 v73, v73
	s_waitcnt lgkmcnt(4)
	v_mfma_f32_32x32x16_bf16 v[0:15], v[148:151], v[108:111], v[0:15]
	v_exp_f32_e32 v74, v74
	v_exp_f32_e32 v75, v75
	s_waitcnt lgkmcnt(2)
	v_mfma_f32_32x32x16_bf16 v[16:31], v[144:147], v[190:193], v[16:31]
	v_exp_f32_e32 v76, v76
	v_exp_f32_e32 v77, v77
	s_waitcnt lgkmcnt(0)
	v_mfma_f32_32x32x16_bf16 v[0:15], v[144:147], v[84:87], v[0:15]
	v_exp_f32_e32 v78, v78
	v_exp_f32_e32 v79, v79
	s_waitcnt vmcnt(0) lgkmcnt(0)
	s_barrier
;   #define RESC() do{ if(!NOMAX&&resc){ asm volatile("s_waitcnt lgkmcnt(0)":::"memory"); \
;       _Pragma("unroll") for(int d_=0;d_<2*VM;++d_) _Pragma("unroll") for(int r=0;r<16;++r)o[d_][r]*=wsf[crow(r,hi)]; } }while(0)
; template<int THRL,int VM,bool NOMAX> __device__ __forceinline__ void attn_unit(const bf16*Qb,const bf16*__restrict__ Kh,const bf16*__restrict__ Vh,bf16*Ob,const int NT,const int sp,float*wscr,char*shm){
;     ...
;   STEP(pB0,pB1,pA0,pA1,NT-1,false,false,false); RESC();
	ds_read_b64_tr_b16 v[170:171], v168 offset:24576
	ds_read_b64_tr_b16 v[172:173], v168 offset:25088
	v_add_f32_e32 v88, v112, v113
	ds_read_b128 v[84:87], v188
	v_add_f32_e32 v88, v114, v88
	v_add_f32_e32 v88, v115, v88
	v_add_f32_e32 v88, v116, v88
	v_add_f32_e32 v104, v117, v88
	v_cvt_pk_bf16_f32 v156, v112, v113
	v_cvt_pk_bf16_f32 v157, v114, v115
	s_waitcnt lgkmcnt(0)
	v_mfma_f32_32x32x16_bf16 v[80:95], v[80:83], v[84:87], 0
	ds_read_b64_tr_b16 v[112:113], v168 offset:28672
	ds_read_b64_tr_b16 v[114:115], v168 offset:29184
	ds_read_b128 v[100:103], v188
	v_add_f32_e32 v104, v118, v104
	v_add_f32_e32 v104, v119, v104
	v_add_f32_e32 v104, v120, v104
	v_add_f32_e32 v144, v121, v104
	v_cvt_pk_bf16_f32 v158, v116, v117
	v_cvt_pk_bf16_f32 v159, v118, v119
	s_waitcnt lgkmcnt(0)
	v_mfma_f32_32x32x16_bf16 v[96:111], v[96:99], v[100:103], 0
	ds_read_b64_tr_b16 v[116:117], v168 offset:25600
	ds_read_b64_tr_b16 v[118:119], v168 offset:26112
	ds_read_b128 v[178:181], v188 offset:1024
	v_add_f32_e32 v144, v122, v144
	v_add_f32_e32 v144, v123, v144
	v_add_f32_e32 v144, v124, v144
	v_add_f32_e32 v144, v125, v144
	v_cvt_pk_bf16_f32 v152, v120, v121
	v_cvt_pk_bf16_f32 v153, v122, v123
	s_waitcnt lgkmcnt(0)
	v_mfma_f32_32x32x16_bf16 v[80:95], v[164:167], v[178:181], v[80:95]
	ds_read_b64_tr_b16 v[120:121], v168 offset:29696
	ds_read_b64_tr_b16 v[122:123], v168 offset:30208
	ds_read_b128 v[164:167], v188 offset:1024
	v_add_f32_e32 v144, v126, v144
	v_add_f32_e32 v144, v127, v144
	v_add_f32_e32 v144, v64, v144
	v_add_f32_e32 v144, v65, v144
	v_cvt_pk_bf16_f32 v154, v124, v125
	v_cvt_pk_bf16_f32 v155, v126, v127
	s_waitcnt lgkmcnt(0)
	v_mfma_f32_32x32x16_bf16 v[96:111], v[140:143], v[164:167], v[96:111]
	ds_read_b64_tr_b16 v[124:125], v168 offset:26624
	ds_read_b64_tr_b16 v[126:127], v168 offset:27136
	ds_read_b128 v[140:143], v188 offset:2048
	v_add_f32_e32 v144, v66, v144
	v_add_f32_e32 v144, v67, v144
	v_add_f32_e32 v144, v68, v144
	v_add_f32_e32 v144, v69, v144
	v_cvt_pk_bf16_f32 v148, v64, v65
	v_cvt_pk_bf16_f32 v149, v66, v67
	s_waitcnt lgkmcnt(0)
	v_mfma_f32_32x32x16_bf16 v[80:95], v[160:163], v[140:143], v[80:95]
	ds_read_b64_tr_b16 v[64:65], v168 offset:30720
	ds_read_b64_tr_b16 v[66:67], v168 offset:31232
	ds_read_b128 v[140:143], v188 offset:2048
	v_add_f32_e32 v144, v70, v144
	v_add_f32_e32 v144, v71, v144
	v_add_f32_e32 v144, v72, v144
	v_add_f32_e32 v144, v73, v144
	v_cvt_pk_bf16_f32 v150, v68, v69
	v_cvt_pk_bf16_f32 v151, v70, v71
	s_waitcnt lgkmcnt(0)
	v_mfma_f32_32x32x16_bf16 v[96:111], v[132:135], v[140:143], v[96:111]
	ds_read_b64_tr_b16 v[68:69], v168 offset:27648
	ds_read_b64_tr_b16 v[70:71], v168 offset:28160
	ds_read_b128 v[132:135], v188 offset:3072
	v_add_f32_e32 v140, v74, v144
	v_add_f32_e32 v140, v75, v140
	v_add_f32_e32 v140, v76, v140
	v_add_f32_e32 v140, v77, v140
	v_cvt_pk_bf16_f32 v144, v72, v73
	v_cvt_pk_bf16_f32 v145, v74, v75
	s_waitcnt lgkmcnt(0)
	v_mfma_f32_32x32x16_bf16 v[80:95], v[136:139], v[132:135], v[80:95]
	ds_read_b64_tr_b16 v[72:73], v168 offset:31744
	ds_read_b64_tr_b16 v[74:75], v168 offset:32256
	ds_read_b128 v[132:135], v188 offset:3072
	v_add_f32_e32 v136, v78, v140
	v_add_f32_e32 v136, v79, v136
	v_add_f32_e32 v136, 0, v136
	v_cvt_pk_bf16_f32 v146, v76, v77
	v_cvt_pk_bf16_f32 v147, v78, v79
	s_waitcnt lgkmcnt(0)
	v_mfma_f32_32x32x16_bf16 v[96:111], v[128:131], v[132:135], v[96:111]
	v_mfma_f32_32x32x16_bf16 v[48:63], v[156:159], v[170:173], v[48:63]
	ds_read_b64_tr_b16 v[76:77], v168 offset:32768
	ds_read_b64_tr_b16 v[78:79], v168 offset:33280
	v_exp_f32_e32 v80, v80
	v_exp_f32_e32 v81, v81
	v_mfma_f32_32x32x16_bf16 v[32:47], v[156:159], v[112:115], v[32:47]
	ds_read_b64_tr_b16 v[128:129], v168 offset:36864
	ds_read_b64_tr_b16 v[130:131], v168 offset:37376
	v_exp_f32_e32 v82, v82
	v_exp_f32_e32 v83, v83
	v_mfma_f32_32x32x16_bf16 v[48:63], v[152:155], v[116:119], v[48:63]
	ds_read_b64_tr_b16 v[112:113], v168 offset:33792
	ds_read_b64_tr_b16 v[114:115], v168 offset:34304
	v_exp_f32_e32 v84, v84
	v_exp_f32_e32 v85, v85
	v_mfma_f32_32x32x16_bf16 v[32:47], v[152:155], v[120:123], v[32:47]
	ds_read_b64_tr_b16 v[116:117], v168 offset:37888
	ds_read_b64_tr_b16 v[118:119], v168 offset:38400
	v_exp_f32_e32 v86, v86
	v_exp_f32_e32 v87, v87
	v_mfma_f32_32x32x16_bf16 v[48:63], v[148:151], v[124:127], v[48:63]
	ds_read_b64_tr_b16 v[120:121], v168 offset:34816
	ds_read_b64_tr_b16 v[122:123], v168 offset:35328
	v_exp_f32_e32 v88, v88
	v_exp_f32_e32 v89, v89
	v_mfma_f32_32x32x16_bf16 v[32:47], v[148:151], v[64:67], v[32:47]
	ds_read_b64_tr_b16 v[124:125], v168 offset:38912
	ds_read_b64_tr_b16 v[126:127], v168 offset:39424
	v_exp_f32_e32 v90, v90
	v_exp_f32_e32 v91, v91
	v_mfma_f32_32x32x16_bf16 v[48:63], v[144:147], v[68:71], v[48:63]
	ds_read_b64_tr_b16 v[64:65], v168 offset:35840
	ds_read_b64_tr_b16 v[66:67], v168 offset:36352
	v_exp_f32_e32 v92, v92
	v_exp_f32_e32 v93, v93
	v_mfma_f32_32x32x16_bf16 v[32:47], v[144:147], v[72:75], v[32:47]
	ds_read_b64_tr_b16 v[68:69], v168 offset:39936
	ds_read_b64_tr_b16 v[70:71], v168 offset:40448
	v_exp_f32_e32 v94, v94
	v_exp_f32_e32 v95, v95
	s_waitcnt lgkmcnt(14)
	v_mfma_f32_32x32x16_bf16 v[16:31], v[156:159], v[76:79], v[16:31]
	v_exp_f32_e32 v96, v96
	v_exp_f32_e32 v97, v97
	s_waitcnt lgkmcnt(12)
; #define SBAR() __builtin_amdgcn_sched_barrier(0)
;   #define RESC() do{ if(!NOMAX&&resc){ asm volatile("s_waitcnt lgkmcnt(0)":::"memory"); \
;       _Pragma("unroll") for(int d_=0;d_<2*VM;++d_) _Pragma("unroll") for(int r=0;r<16;++r)o[d_][r]*=wsf[crow(r,hi)]; } }while(0)
;   #define PKW(P,B) cvtpk_s(P[B],P[B+1])
; __device__ __forceinline__ void pv(f32x16*o,int vb,bf16x8 pa0,bf16x8 pa1,bf16x8 pa2,bf16x8 pa3){
;   #pragma unroll
;   for(int d0=0;d0<2;++d0){s16x4 lo[4],hi[4];
;     #pragma unroll
;     for(int ks=0;ks<4;++ks){
;       asm volatile("ds_read_b64_tr_b16 %0,%1 offset:%c2":"=&v"(lo[ks]):"v"(vb),"i"(d0*4096+ks*1024):"memory");
;       asm volatile("ds_read_b64_tr_b16 %0,%1 offset:%c2":"=&v"(hi[ks]):"v"(vb),"i"(d0*4096+ks*1024+512):"memory");}
;     asm volatile("s_waitcnt lgkmcnt(0)":::"memory");SBAR();
;     ...
;     o[d0]=__builtin_amdgcn_mfma_f32_32x32x16_bf16(pa0,PK(0),o[d0],0,0,0);
;     o[d0]=__builtin_amdgcn_mfma_f32_32x32x16_bf16(pa1,PK(1),o[d0],0,0,0);
;     o[d0]=__builtin_amdgcn_mfma_f32_32x32x16_bf16(pa2,PK(2),o[d0],0,0,0);
;     o[d0]=__builtin_amdgcn_mfma_f32_32x32x16_bf16(pa3,PK(3),o[d0],0,0,0);
;     ...
;   }
; }
; template<int THRL,int VM,bool NOMAX> __device__ __forceinline__ void attn_unit(const bf16*Qb,const bf16*__restrict__ Kh,const bf16*__restrict__ Vh,bf16*Ob,const int NT,const int sp,float*wscr,char*shm){
;     ...
;   STEP(pB0,pB1,pA0,pA1,NT-1,false,false,false); RESC();
;   { float sacc=pB0[0]+pB0[1]; _Pragma("unroll") for(int r=2;r<16;++r)sacc+=pB0[r]; _Pragma("unroll") for(int r=0;r<16;++r)sacc+=pB1[r]; l_reg+=sacc;
;     pw0=(u32x4){PKW(pB0,0),PKW(pB0,2),PKW(pB0,4),PKW(pB0,6)};pw1=(u32x4){PKW(pB0,8),PKW(pB0,10),PKW(pB0,12),PKW(pB0,14)};pw2=(u32x4){PKW(pB1,0),PKW(pB1,2),PKW(pB1,4),PKW(pB1,6)};pw3=(u32x4){PKW(pB1,8),PKW(pB1,10),PKW(pB1,12),PKW(pB1,14)};
;     SBAR(); pv(o,vb0+VM*sl_cur,PAF(0),PAF(1),PAF(2),PAF(3)); if constexpr(VM==2) pv(o+2,vb0+VM*sl_cur+8192,PAF(0),PAF(1),PAF(2),PAF(3)); }
;     ...
;   {auto rr=__builtin_amdgcn_permlane32_swap(__float_as_uint(l_reg),__float_as_uint(l_reg),false,false);l_reg=__uint_as_float(rr[0])+__uint_as_float(rr[1]);}
;   if(hi==0)wsf[32+r32]=l_reg;asm volatile("s_waitcnt lgkmcnt(0)":::"memory");
	v_mfma_f32_32x32x16_bf16 v[0:15], v[156:159], v[128:131], v[0:15]
	v_exp_f32_e32 v98, v98
	v_exp_f32_e32 v99, v99
	s_waitcnt lgkmcnt(10)
	v_mfma_f32_32x32x16_bf16 v[16:31], v[152:155], v[112:115], v[16:31]
	v_exp_f32_e32 v100, v100
	v_exp_f32_e32 v101, v101
	s_waitcnt lgkmcnt(8)
	v_mfma_f32_32x32x16_bf16 v[0:15], v[152:155], v[116:119], v[0:15]
	v_exp_f32_e32 v102, v102
	v_exp_f32_e32 v103, v103
	s_waitcnt lgkmcnt(6)
	v_mfma_f32_32x32x16_bf16 v[16:31], v[148:151], v[120:123], v[16:31]
	v_exp_f32_e32 v104, v104
	v_exp_f32_e32 v105, v105
	s_waitcnt lgkmcnt(4)
	v_mfma_f32_32x32x16_bf16 v[0:15], v[148:151], v[124:127], v[0:15]
	v_exp_f32_e32 v106, v106
	v_exp_f32_e32 v107, v107
	s_waitcnt lgkmcnt(2)
	v_mfma_f32_32x32x16_bf16 v[16:31], v[144:147], v[64:67], v[16:31]
	v_exp_f32_e32 v108, v108
	v_exp_f32_e32 v109, v109
	s_waitcnt lgkmcnt(0)
	v_mfma_f32_32x32x16_bf16 v[0:15], v[144:147], v[68:71], v[0:15]
	v_exp_f32_e32 v110, v110
	v_exp_f32_e32 v111, v111
	v_add_f32_e32 v64, v80, v81
	v_add_f32_e32 v64, v82, v64
	v_add_f32_e32 v64, v83, v64
	v_add_f32_e32 v64, v84, v64
	v_add_f32_e32 v64, v85, v64
	v_add_f32_e32 v64, v86, v64
	v_add_f32_e32 v64, v87, v64
	v_add_f32_e32 v64, v88, v64
	v_add_f32_e32 v64, v89, v64
	v_add_f32_e32 v64, v90, v64
	v_add_f32_e32 v64, v91, v64
	v_add_f32_e32 v64, v92, v64
	v_add_f32_e32 v64, v93, v64
	v_add_f32_e32 v64, v94, v64
	v_add_f32_e32 v64, v95, v64
	v_add_f32_e32 v64, v64, v96
	v_add_f32_e32 v64, v97, v64
	v_add_f32_e32 v64, v98, v64
	v_add_f32_e32 v64, v99, v64
	v_add_f32_e32 v64, v100, v64
	v_add_f32_e32 v64, v101, v64
	v_add_f32_e32 v64, v102, v64
	v_add_f32_e32 v64, v103, v64
	v_add_f32_e32 v64, v104, v64
	v_add_f32_e32 v64, v105, v64
	v_add_f32_e32 v64, v106, v64
	v_add_f32_e32 v64, v107, v64
	v_add_f32_e32 v64, v108, v64
	v_add_f32_e32 v64, v109, v64
	v_add_f32_e32 v64, v110, v64
	v_add_f32_e32 v64, v111, v64
	v_add_f32_e32 v65, v174, v136
	v_add_f32_e32 v64, v65, v64
	v_cvt_pk_bf16_f32 v66, v80, v81
	v_cvt_pk_bf16_f32 v67, v82, v83
	v_cvt_pk_bf16_f32 v68, v84, v85
	v_cvt_pk_bf16_f32 v69, v86, v87
	v_cvt_pk_bf16_f32 v70, v88, v89
	v_cvt_pk_bf16_f32 v71, v90, v91
	v_cvt_pk_bf16_f32 v72, v92, v93
	v_cvt_pk_bf16_f32 v73, v94, v95
	v_cvt_pk_bf16_f32 v74, v96, v97
	v_cvt_pk_bf16_f32 v75, v98, v99
	v_cvt_pk_bf16_f32 v76, v100, v101
	v_cvt_pk_bf16_f32 v77, v102, v103
	v_cvt_pk_bf16_f32 v78, v104, v105
	v_cvt_pk_bf16_f32 v79, v106, v107
	v_cvt_pk_bf16_f32 v80, v108, v109
	v_cvt_pk_bf16_f32 v81, v110, v111
	v_add_u32_e32 v65, 0x4000, v176
	ds_read_b64_tr_b16 v[82:83],v65 offset:0
	ds_read_b64_tr_b16 v[84:85],v65 offset:512
	ds_read_b64_tr_b16 v[86:87],v65 offset:1024
	ds_read_b64_tr_b16 v[88:89],v65 offset:1536
	ds_read_b64_tr_b16 v[90:91],v65 offset:2048
	ds_read_b64_tr_b16 v[92:93],v65 offset:2560
	ds_read_b64_tr_b16 v[94:95],v65 offset:3072
	ds_read_b64_tr_b16 v[96:97],v65 offset:3584
	s_waitcnt lgkmcnt(0)
	s_nop 0
	v_mfma_f32_32x32x16_bf16 v[48:63], v[66:69], v[82:85], v[48:63]
	ds_read_b64_tr_b16 v[82:83],v65 offset:4096
	ds_read_b64_tr_b16 v[84:85],v65 offset:4608
	v_mfma_f32_32x32x16_bf16 v[48:63], v[70:73], v[86:89], v[48:63]
	ds_read_b64_tr_b16 v[86:87],v65 offset:5120
	ds_read_b64_tr_b16 v[88:89],v65 offset:5632
	v_mfma_f32_32x32x16_bf16 v[48:63], v[74:77], v[90:93], v[48:63]
	ds_read_b64_tr_b16 v[90:91],v65 offset:6144
	ds_read_b64_tr_b16 v[92:93],v65 offset:6656
	ds_read_b64_tr_b16 v[98:99],v65 offset:7168
	ds_read_b64_tr_b16 v[100:101],v65 offset:7680
	s_waitcnt lgkmcnt(0)
	v_mfma_f32_32x32x16_bf16 v[48:63], v[78:81], v[94:97], v[48:63]
	v_mfma_f32_32x32x16_bf16 v[32:47], v[66:69], v[82:85], v[32:47]
	v_add_u32_e32 v65, 0x6000, v176
	ds_read_b64_tr_b16 v[82:83],v65 offset:0
	ds_read_b64_tr_b16 v[84:85],v65 offset:512
	v_mfma_f32_32x32x16_bf16 v[32:47], v[70:73], v[86:89], v[32:47]
	ds_read_b64_tr_b16 v[86:87],v65 offset:1024
	ds_read_b64_tr_b16 v[88:89],v65 offset:1536
	v_mfma_f32_32x32x16_bf16 v[32:47], v[74:77], v[90:93], v[32:47]
	ds_read_b64_tr_b16 v[90:91],v65 offset:2048
	ds_read_b64_tr_b16 v[92:93],v65 offset:2560
	ds_read_b64_tr_b16 v[94:95],v65 offset:3072
	ds_read_b64_tr_b16 v[96:97],v65 offset:3584
	s_waitcnt lgkmcnt(0)
	v_mfma_f32_32x32x16_bf16 v[32:47], v[78:81], v[98:101], v[32:47]
	v_mfma_f32_32x32x16_bf16 v[16:31], v[66:69], v[82:85], v[16:31]
	ds_read_b64_tr_b16 v[82:83],v65 offset:4096
	ds_read_b64_tr_b16 v[84:85],v65 offset:4608
	v_mfma_f32_32x32x16_bf16 v[16:31], v[70:73], v[86:89], v[16:31]
	ds_read_b64_tr_b16 v[86:87],v65 offset:5120
	ds_read_b64_tr_b16 v[88:89],v65 offset:5632
	v_mfma_f32_32x32x16_bf16 v[16:31], v[74:77], v[90:93], v[16:31]
	ds_read_b64_tr_b16 v[90:91],v65 offset:6144
	ds_read_b64_tr_b16 v[92:93],v65 offset:6656
	ds_read_b64_tr_b16 v[98:99],v65 offset:7168
	ds_read_b64_tr_b16 v[100:101],v65 offset:7680
	s_waitcnt lgkmcnt(0)
	v_mfma_f32_32x32x16_bf16 v[16:31], v[78:81], v[94:97], v[16:31]
	v_mfma_f32_32x32x16_bf16 v[0:15], v[66:69], v[82:85], v[0:15]
	v_mov_b32_e32 v65, v64
	s_nop 1
	v_permlane32_swap_b32_e32 v64, v65
	v_cmp_gt_u32_e32 vcc, 32, v187
	v_mfma_f32_32x32x16_bf16 v[0:15], v[70:73], v[86:89], v[0:15]
	v_mfma_f32_32x32x16_bf16 v[0:15], v[74:77], v[90:93], v[0:15]
	v_mfma_f32_32x32x16_bf16 v[0:15], v[78:81], v[98:101], v[0:15]
	s_and_saveexec_b64 s[16:17], vcc
	s_cbranch_execz .LBB0_859
	v_add_f32_e32 v64, v64, v65
	v_lshl_add_u32 v65, v186, 2, s34
	ds_write_b32 v65, v64 offset:128
	s_branch .LBB0_859

.LBB0_874:
	v_mfma_f32_32x32x16_bf16 v[112:127], v[100:103], v[218:221], 0
	v_lshl_add_u32 v206, s89, 1, v188
	ds_read_b64_tr_b16 v[194:195], v206 offset:24576
	ds_read_b64_tr_b16 v[196:197], v206 offset:25088
	v_add_f32_e32 v108, v80, v81
	v_add_f32_e32 v108, v82, v108
	v_add_f32_e32 v108, v83, v108
	v_add_f32_e32 v108, v84, v108
	v_add_f32_e32 v108, v85, v108
	v_cvt_pk_bf16_f32 v156, v80, v81
	v_cvt_pk_bf16_f32 v157, v82, v83
	ds_read_b64_tr_b16 v[80:81], v206 offset:28672
	ds_read_b64_tr_b16 v[82:83], v206 offset:29184
	v_add_f32_e32 v104, v86, v108
	v_add_f32_e32 v104, v87, v104
	v_add_f32_e32 v104, v88, v104
	v_add_f32_e32 v144, v89, v104
	v_mfma_f32_32x32x16_bf16 v[96:111], v[96:99], v[218:221], 0
	v_cvt_pk_bf16_f32 v158, v84, v85
	v_cvt_pk_bf16_f32 v159, v86, v87
	ds_read_b64_tr_b16 v[84:85], v206 offset:25600
	ds_read_b64_tr_b16 v[86:87], v206 offset:26112
	v_add_f32_e32 v144, v90, v144
	v_add_f32_e32 v144, v91, v144
	v_add_f32_e32 v144, v92, v144
	v_add_f32_e32 v144, v93, v144
	v_cvt_pk_bf16_f32 v152, v88, v89
	v_cvt_pk_bf16_f32 v153, v90, v91
	v_mfma_f32_32x32x16_bf16 v[112:127], v[164:167], v[222:225], v[112:127]
	ds_read_b64_tr_b16 v[88:89], v206 offset:29696
	ds_read_b64_tr_b16 v[90:91], v206 offset:30208
	v_add_f32_e32 v144, v94, v144
	v_add_f32_e32 v144, v95, v144
	v_add_f32_e32 v144, v64, v144
	v_add_f32_e32 v144, v65, v144
	v_mfma_f32_32x32x16_bf16 v[96:111], v[160:163], v[222:225], v[96:111]
	v_cvt_pk_bf16_f32 v154, v92, v93
	v_cvt_pk_bf16_f32 v155, v94, v95
	ds_read_b64_tr_b16 v[92:93], v206 offset:26624
	ds_read_b64_tr_b16 v[94:95], v206 offset:27136
	v_add_f32_e32 v144, v66, v144
	v_add_f32_e32 v144, v67, v144
	v_add_f32_e32 v144, v68, v144
	v_add_f32_e32 v144, v69, v144
	v_cvt_pk_bf16_f32 v148, v64, v65
	v_cvt_pk_bf16_f32 v149, v66, v67
	v_mfma_f32_32x32x16_bf16 v[112:127], v[140:143], v[226:229], v[112:127]
	ds_read_b64_tr_b16 v[198:199], v206 offset:30720
	ds_read_b64_tr_b16 v[200:201], v206 offset:31232
	v_add_f32_e32 v140, v70, v144
	v_add_f32_e32 v140, v71, v140
	v_add_f32_e32 v140, v72, v140
	v_add_f32_e32 v140, v73, v140
	v_mfma_f32_32x32x16_bf16 v[96:111], v[136:139], v[226:229], v[96:111]
	v_cvt_pk_bf16_f32 v150, v68, v69
	v_cvt_pk_bf16_f32 v151, v70, v71
	ds_read_b64_tr_b16 v[202:203], v206 offset:27648
	ds_read_b64_tr_b16 v[204:205], v206 offset:28160
	v_add_f32_e32 v68, v74, v140
	v_add_f32_e32 v68, v75, v68
	v_add_f32_e32 v68, v76, v68
	v_add_f32_e32 v68, v77, v68
	v_cvt_pk_bf16_f32 v144, v72, v73
	v_cvt_pk_bf16_f32 v145, v74, v75
	v_mfma_f32_32x32x16_bf16 v[112:127], v[132:135], v[230:233], v[112:127]
	ds_read_b64_tr_b16 v[72:73], v206 offset:31744
	ds_read_b64_tr_b16 v[74:75], v206 offset:32256
	v_add_f32_e32 v68, v78, v68
	v_add_f32_e32 v68, v79, v68
	v_add_f32_e32 v68, 0, v68
	v_cvt_pk_bf16_f32 v146, v76, v77
	v_mfma_f32_32x32x16_bf16 v[96:111], v[128:131], v[230:233], v[96:111]
	v_cvt_pk_bf16_f32 v147, v78, v79
	s_add_i32 s88, s87, s17
	v_lshl_add_u64 v[64:65], v[180:181], 0, s[56:57]
	s_mov_b32 s89, m0
	s_mov_b32 m0, s88
	s_nop 0
	global_load_lds_dwordx4 v[64:65], off
	s_mov_b32 m0, s89
	s_lshl_b32 s88, s86, 1
	v_lshl_add_u64 v[64:65], v[178:179], 0, s[56:57]
	s_add_i32 s88, s88, s16
	s_mov_b32 s89, m0
	s_mov_b32 m0, s88
	s_nop 0
	global_load_lds_dwordx4 v[64:65], off
	s_mov_b32 m0, s89
	v_lshl_add_u64 v[64:65], v[176:177], 0, s[56:57]
	s_addk_i32 s88, 0x2000
	s_mov_b32 s89, m0
	s_mov_b32 m0, s88
	s_nop 0
	global_load_lds_dwordx4 v[64:65], off
	s_mov_b32 m0, s89
	v_add_f32_e32 v193, v193, v68
	v_add_u32_e32 v242, s86, v234
	v_add_u32_e32 v243, s86, v235
	v_add_u32_e32 v244, s86, v236
	v_add_u32_e32 v245, s86, v237
	s_waitcnt lgkmcnt(12)
	v_mfma_f32_32x32x16_bf16 v[48:63], v[156:159], v[194:197], v[48:63]
	ds_read_b64_tr_b16 v[76:77], v206 offset:32768
	ds_read_b64_tr_b16 v[78:79], v206 offset:33280
	v_exp_f32_e32 v112, v112
	v_exp_f32_e32 v113, v113
	ds_read_b128 v[68:71], v242
	v_mfma_f32_32x32x16_bf16 v[32:47], v[156:159], v[80:83], v[32:47]
	ds_read_b64_tr_b16 v[194:195], v206 offset:36864
	ds_read_b64_tr_b16 v[196:197], v206 offset:37376
	v_exp_f32_e32 v114, v114
	v_exp_f32_e32 v115, v115
	ds_read_b128 v[64:67], v242 offset:4096
	s_waitcnt lgkmcnt(14)
	v_mfma_f32_32x32x16_bf16 v[48:63], v[152:155], v[84:87], v[48:63]
	ds_read_b64_tr_b16 v[80:81], v206 offset:33792
	ds_read_b64_tr_b16 v[82:83], v206 offset:34304
	v_exp_f32_e32 v116, v116
	v_exp_f32_e32 v117, v117
	ds_read_b128 v[164:167], v243
	v_mfma_f32_32x32x16_bf16 v[32:47], v[152:155], v[88:91], v[32:47]
	ds_read_b64_tr_b16 v[84:85], v206 offset:37888
	ds_read_b64_tr_b16 v[86:87], v206 offset:38400
	v_exp_f32_e32 v118, v118
	v_exp_f32_e32 v119, v119
	ds_read_b128 v[140:143], v243 offset:4096
	s_waitcnt lgkmcnt(14)
	v_mfma_f32_32x32x16_bf16 v[48:63], v[148:151], v[92:95], v[48:63]
	ds_read_b64_tr_b16 v[88:89], v206 offset:34816
	ds_read_b64_tr_b16 v[90:91], v206 offset:35328
	v_exp_f32_e32 v120, v120
	v_exp_f32_e32 v121, v121
	ds_read_b128 v[160:163], v244
	v_mfma_f32_32x32x16_bf16 v[32:47], v[148:151], v[198:201], v[32:47]
	ds_read_b64_tr_b16 v[92:93], v206 offset:38912
	ds_read_b64_tr_b16 v[94:95], v206 offset:39424
	v_exp_f32_e32 v122, v122
	v_exp_f32_e32 v123, v123
	ds_read_b128 v[132:135], v244 offset:4096
	s_waitcnt lgkmcnt(14)
	v_mfma_f32_32x32x16_bf16 v[48:63], v[144:147], v[202:205], v[48:63]
	ds_read_b64_tr_b16 v[198:199], v206 offset:35840
	ds_read_b64_tr_b16 v[200:201], v206 offset:36352
	v_exp_f32_e32 v124, v124
	v_exp_f32_e32 v125, v125
	ds_read_b128 v[136:139], v245
	v_mfma_f32_32x32x16_bf16 v[32:47], v[144:147], v[72:75], v[32:47]
	ds_read_b64_tr_b16 v[202:203], v206 offset:39936
	ds_read_b64_tr_b16 v[204:205], v206 offset:40448
	v_exp_f32_e32 v126, v126
	v_exp_f32_e32 v127, v127
	ds_read_b128 v[128:131], v245 offset:4096
	s_waitcnt lgkmcnt(14)
	v_mfma_f32_32x32x16_bf16 v[16:31], v[156:159], v[76:79], v[16:31]
	v_exp_f32_e32 v96, v96
	v_exp_f32_e32 v97, v97
	v_mfma_f32_32x32x16_bf16 v[0:15], v[156:159], v[194:197], v[0:15]
	v_exp_f32_e32 v98, v98
	v_exp_f32_e32 v99, v99
	v_mfma_f32_32x32x16_bf16 v[16:31], v[152:155], v[80:83], v[16:31]
	v_exp_f32_e32 v100, v100
	v_exp_f32_e32 v101, v101
	s_waitcnt lgkmcnt(12)
	v_mfma_f32_32x32x16_bf16 v[0:15], v[152:155], v[84:87], v[0:15]
	v_exp_f32_e32 v102, v102
	v_exp_f32_e32 v103, v103
	s_waitcnt lgkmcnt(8)
	v_mfma_f32_32x32x16_bf16 v[16:31], v[148:151], v[88:91], v[16:31]
	v_exp_f32_e32 v104, v104
	v_exp_f32_e32 v105, v105
	s_waitcnt lgkmcnt(4)
	v_mfma_f32_32x32x16_bf16 v[0:15], v[148:151], v[92:95], v[0:15]
	v_exp_f32_e32 v106, v106
	v_exp_f32_e32 v107, v107
	s_waitcnt lgkmcnt(2)
	v_mfma_f32_32x32x16_bf16 v[16:31], v[144:147], v[198:201], v[16:31]
	v_exp_f32_e32 v108, v108
	v_exp_f32_e32 v109, v109
	s_waitcnt lgkmcnt(0)
	v_mfma_f32_32x32x16_bf16 v[0:15], v[144:147], v[202:205], v[0:15]
	v_exp_f32_e32 v110, v110
	v_exp_f32_e32 v111, v111
	s_waitcnt vmcnt(3) lgkmcnt(0)
	s_barrier
	v_mfma_f32_32x32x16_bf16 v[80:95], v[68:71], v[218:221], 0
	s_add_i32 s88, s86, 0x2000
	s_cmpk_lg_i32 s86, 0x4000
	s_cselect_b32 s88, s88, 0
	v_lshl_add_u32 v206, s87, 1, v188
	ds_read_b64_tr_b16 v[194:195], v206 offset:24576
	ds_read_b64_tr_b16 v[196:197], v206 offset:25088
	v_add_f32_e32 v76, v112, v113
	v_add_f32_e32 v76, v114, v76
	v_add_f32_e32 v76, v115, v76
	v_add_f32_e32 v76, v116, v76
	v_add_f32_e32 v76, v117, v76
	v_cvt_pk_bf16_f32 v156, v112, v113
	v_cvt_pk_bf16_f32 v157, v114, v115
	ds_read_b64_tr_b16 v[112:113], v206 offset:28672
	ds_read_b64_tr_b16 v[114:115], v206 offset:29184
	v_add_f32_e32 v72, v118, v76
	v_add_f32_e32 v72, v119, v72
	v_add_f32_e32 v72, v120, v72
	v_add_f32_e32 v144, v121, v72
	v_mfma_f32_32x32x16_bf16 v[64:79], v[64:67], v[218:221], 0
	v_cvt_pk_bf16_f32 v158, v116, v117
	v_cvt_pk_bf16_f32 v159, v118, v119
	ds_read_b64_tr_b16 v[116:117], v206 offset:25600
	ds_read_b64_tr_b16 v[118:119], v206 offset:26112
	v_add_f32_e32 v144, v122, v144
	v_add_f32_e32 v144, v123, v144
	v_add_f32_e32 v144, v124, v144
	v_add_f32_e32 v144, v125, v144
	v_mfma_f32_32x32x16_bf16 v[80:95], v[164:167], v[222:225], v[80:95]
	v_cvt_pk_bf16_f32 v152, v120, v121
	v_cvt_pk_bf16_f32 v153, v122, v123
	ds_read_b64_tr_b16 v[120:121], v206 offset:29696
	ds_read_b64_tr_b16 v[122:123], v206 offset:30208
	v_add_f32_e32 v144, v126, v144
	v_add_f32_e32 v144, v127, v144
	v_add_f32_e32 v144, v96, v144
	v_add_f32_e32 v144, v97, v144
	v_mfma_f32_32x32x16_bf16 v[64:79], v[140:143], v[222:225], v[64:79]
	v_cvt_pk_bf16_f32 v154, v124, v125
	v_cvt_pk_bf16_f32 v155, v126, v127
	ds_read_b64_tr_b16 v[124:125], v206 offset:26624
	ds_read_b64_tr_b16 v[126:127], v206 offset:27136
	v_add_f32_e32 v144, v98, v144
	v_add_f32_e32 v144, v99, v144
	v_add_f32_e32 v144, v100, v144
	v_add_f32_e32 v144, v101, v144
	v_mfma_f32_32x32x16_bf16 v[80:95], v[160:163], v[226:229], v[80:95]
	v_cvt_pk_bf16_f32 v148, v96, v97
	v_cvt_pk_bf16_f32 v149, v98, v99
	ds_read_b64_tr_b16 v[198:199], v206 offset:30720
	ds_read_b64_tr_b16 v[200:201], v206 offset:31232
	v_add_f32_e32 v140, v102, v144
	v_add_f32_e32 v140, v103, v140
	v_add_f32_e32 v140, v104, v140
	v_add_f32_e32 v140, v105, v140
	v_mfma_f32_32x32x16_bf16 v[64:79], v[132:135], v[226:229], v[64:79]
	v_cvt_pk_bf16_f32 v150, v100, v101
	v_cvt_pk_bf16_f32 v151, v102, v103
	ds_read_b64_tr_b16 v[202:203], v206 offset:27648
	ds_read_b64_tr_b16 v[204:205], v206 offset:28160
	v_add_f32_e32 v100, v106, v140
	v_add_f32_e32 v100, v107, v100
	v_add_f32_e32 v100, v108, v100
	v_add_f32_e32 v100, v109, v100
	v_mfma_f32_32x32x16_bf16 v[80:95], v[136:139], v[230:233], v[80:95]
	v_cvt_pk_bf16_f32 v144, v104, v105
	v_cvt_pk_bf16_f32 v145, v106, v107
	ds_read_b64_tr_b16 v[104:105], v206 offset:31744
	ds_read_b64_tr_b16 v[106:107], v206 offset:32256
	v_add_f32_e32 v100, v110, v100
	v_add_f32_e32 v100, v111, v100
	v_add_f32_e32 v100, 0, v100
	v_cvt_pk_bf16_f32 v146, v108, v109
	v_mfma_f32_32x32x16_bf16 v[64:79], v[128:131], v[230:233], v[64:79]
	v_cvt_pk_bf16_f32 v147, v110, v111
	s_add_i32 s87, s86, s17
	s_mov_b32 s89, m0
	s_mov_b32 m0, s87
	s_nop 0
	global_load_lds_dwordx4 v[180:181], off
	s_mov_b32 m0, s89
	s_lshl_b32 s87, s88, 1
	s_add_i32 s87, s87, s16
	s_mov_b32 s89, m0
	s_mov_b32 m0, s87
	s_nop 0
	global_load_lds_dwordx4 v[178:179], off
	s_mov_b32 m0, s89
	s_addk_i32 s87, 0x2000
	s_mov_b32 s89, m0
	s_mov_b32 m0, s87
	s_nop 0
	global_load_lds_dwordx4 v[176:177], off
	s_mov_b32 m0, s89
	v_add_f32_e32 v193, v193, v100
	v_add_u32_e32 v242, s88, v234
	v_add_u32_e32 v243, s88, v235
	v_add_u32_e32 v244, s88, v236
	v_add_u32_e32 v245, s88, v237
	s_waitcnt lgkmcnt(12)
	v_mfma_f32_32x32x16_bf16 v[48:63], v[156:159], v[194:197], v[48:63]
	ds_read_b64_tr_b16 v[108:109], v206 offset:32768
	ds_read_b64_tr_b16 v[110:111], v206 offset:33280
	v_exp_f32_e32 v80, v80
	v_exp_f32_e32 v81, v81
	ds_read_b128 v[100:103], v242
	v_mfma_f32_32x32x16_bf16 v[32:47], v[156:159], v[112:115], v[32:47]
	ds_read_b64_tr_b16 v[194:195], v206 offset:36864
	ds_read_b64_tr_b16 v[196:197], v206 offset:37376
	v_exp_f32_e32 v82, v82
	v_exp_f32_e32 v83, v83
	ds_read_b128 v[96:99], v242 offset:4096
	s_waitcnt lgkmcnt(14)
	v_mfma_f32_32x32x16_bf16 v[48:63], v[152:155], v[116:119], v[48:63]
	ds_read_b64_tr_b16 v[112:113], v206 offset:33792
	ds_read_b64_tr_b16 v[114:115], v206 offset:34304
	v_exp_f32_e32 v84, v84
	v_exp_f32_e32 v85, v85
	ds_read_b128 v[164:167], v243
	v_mfma_f32_32x32x16_bf16 v[32:47], v[152:155], v[120:123], v[32:47]
	ds_read_b64_tr_b16 v[116:117], v206 offset:37888
	ds_read_b64_tr_b16 v[118:119], v206 offset:38400
	v_exp_f32_e32 v86, v86
	v_exp_f32_e32 v87, v87
	ds_read_b128 v[160:163], v243 offset:4096
	s_waitcnt lgkmcnt(14)
	v_mfma_f32_32x32x16_bf16 v[48:63], v[148:151], v[124:127], v[48:63]
	ds_read_b64_tr_b16 v[120:121], v206 offset:34816
	ds_read_b64_tr_b16 v[122:123], v206 offset:35328
	v_exp_f32_e32 v88, v88
	v_exp_f32_e32 v89, v89
	ds_read_b128 v[140:143], v244
	v_mfma_f32_32x32x16_bf16 v[32:47], v[148:151], v[198:201], v[32:47]
	ds_read_b64_tr_b16 v[124:125], v206 offset:38912
	ds_read_b64_tr_b16 v[126:127], v206 offset:39424
	v_exp_f32_e32 v90, v90
	v_exp_f32_e32 v91, v91
	ds_read_b128 v[136:139], v244 offset:4096
	s_waitcnt lgkmcnt(14)
	v_mfma_f32_32x32x16_bf16 v[48:63], v[144:147], v[202:205], v[48:63]
	ds_read_b64_tr_b16 v[198:199], v206 offset:35840
	ds_read_b64_tr_b16 v[200:201], v206 offset:36352
	v_exp_f32_e32 v92, v92
	v_exp_f32_e32 v93, v93
	ds_read_b128 v[132:135], v245
	v_mfma_f32_32x32x16_bf16 v[32:47], v[144:147], v[104:107], v[32:47]
	ds_read_b64_tr_b16 v[202:203], v206 offset:39936
	ds_read_b64_tr_b16 v[204:205], v206 offset:40448
	v_exp_f32_e32 v94, v94
	v_exp_f32_e32 v95, v95
	ds_read_b128 v[128:131], v245 offset:4096
	s_waitcnt lgkmcnt(14)
	v_mfma_f32_32x32x16_bf16 v[16:31], v[156:159], v[108:111], v[16:31]
	v_exp_f32_e32 v64, v64
	v_exp_f32_e32 v65, v65
	v_mfma_f32_32x32x16_bf16 v[0:15], v[156:159], v[194:197], v[0:15]
	v_exp_f32_e32 v66, v66
	v_exp_f32_e32 v67, v67
	v_mfma_f32_32x32x16_bf16 v[16:31], v[152:155], v[112:115], v[16:31]
	v_exp_f32_e32 v68, v68
	v_exp_f32_e32 v69, v69
	s_waitcnt lgkmcnt(12)
	v_mfma_f32_32x32x16_bf16 v[0:15], v[152:155], v[116:119], v[0:15]
	v_exp_f32_e32 v70, v70
	v_exp_f32_e32 v71, v71
	s_waitcnt lgkmcnt(8)
	v_mfma_f32_32x32x16_bf16 v[16:31], v[148:151], v[120:123], v[16:31]
	v_exp_f32_e32 v72, v72
	v_exp_f32_e32 v73, v73
	s_waitcnt lgkmcnt(4)
	v_mfma_f32_32x32x16_bf16 v[0:15], v[148:151], v[124:127], v[0:15]
	v_exp_f32_e32 v74, v74
	v_exp_f32_e32 v75, v75
	s_waitcnt lgkmcnt(2)
	v_mfma_f32_32x32x16_bf16 v[16:31], v[144:147], v[198:201], v[16:31]
	v_exp_f32_e32 v76, v76
	v_exp_f32_e32 v77, v77
	s_waitcnt lgkmcnt(0)
	v_mfma_f32_32x32x16_bf16 v[0:15], v[144:147], v[202:205], v[0:15]
	v_exp_f32_e32 v78, v78
	v_exp_f32_e32 v79, v79
	s_add_i32 s90, s88, 0x2000
	s_waitcnt vmcnt(3) lgkmcnt(0)
	s_barrier
; #define WAIT_BAR(N) asm volatile("s_waitcnt vmcnt(" #N ") lgkmcnt(0)\n\ts_barrier":::"memory")
;   #define RESC() do{ if(!NOMAX&&resc){ asm volatile("s_waitcnt lgkmcnt(0)":::"memory"); \
;       _Pragma("unroll") for(int d_=0;d_<2*VM;++d_) _Pragma("unroll") for(int r=0;r<16;++r)o[d_][r]*=wsf[crow(r,hi)]; } }while(0)
;   #define ROT() do{sl_prev=sl_cur;sl_cur=sl_next;sl_next=(sl_next==(NSLOT-1)*SLOTB)?0:sl_next+SLOTB;}while(0)
;   #define ENDW(tt) do{ if((tt)+3<NT){ if constexpr(VM==2){WAIT_BAR(3);}else{WAIT_BAR(2);} } else if((tt)+2<NT){ if constexpr(VM==2){WAIT_BAR(2);}else{WAIT_BAR(1);} } else {WAIT_BAR(0);} }while(0)
; template<int THRL,int VM,bool NOMAX> __device__ __forceinline__ void attn_unit(const bf16*Qb,const bf16*__restrict__ Kh,const bf16*__restrict__ Vh,bf16*Ob,const int NT,const int sp,float*wscr,char*shm){
;     ...
;   for(;t+5<NT;t+=2){
;     STEP(pB0,pB1,pA0,pA1,t,true,true,true);     if constexpr(VM==2){WAIT_BAR(3);}else{WAIT_BAR(2);} RESC(); ROT();
;     STEP(pA0,pA1,pB0,pB1,t+1,true,true,true);   if constexpr(VM==2){WAIT_BAR(3);}else{WAIT_BAR(2);} RESC(); ROT();
;   }
;     ...
;   for(;t+1<NT;t+=2){
;     STEP(pB0,pB1,pA0,pA1,t,(t+3<NT),(t+1<NT),(t+1<NT));       ENDW(t);   RESC(); ROT();
;     STEP(pA0,pA1,pB0,pB1,t+1,(t+4<NT),(t+2<NT),(t+2<NT));     ENDW(t+1); RESC(); ROT();
	s_cmpk_lg_i32 s88, 0x4000
	s_mov_b32 s89, s86
	s_cselect_b32 s86, s90, 0
	s_add_i32 s85, s85, 2
	v_lshl_add_u64 v[176:177], v[176:177], 0, s[58:59]
	v_lshl_add_u64 v[178:179], v[178:179], 0, s[58:59]
	v_lshl_add_u64 v[180:181], v[180:181], 0, s[58:59]
	s_mov_b32 s87, s88
	s_cmp_lt_u32 s85, 57
	s_cbranch_scc1 .LBB0_874
	s_and_b32 s34, s34, 0x3fffffc0
	s_lshl_b32 s34, s34, 2
	s_add_i32 s34, s34, 0
	s_add_i32 s34, s34, 0x12000
	s_cmp_lg_u32 0, -1
	s_cselect_b32 s85, 0, 0
	s_add_i32 s86, s85, 0x6000
	v_add_u32_e32 v104, s86, v191
	v_add3_u32 v176, v104, v190, v192
	v_add_u32_e32 v177, 0x6000, v188
	ds_read_b64_tr_b16 v[178:179], v188 offset:40960
	ds_read_b64_tr_b16 v[180:181], v188 offset:41472
	v_add_f32_e32 v108, v80, v81
	ds_read_b128 v[104:107], v168
	v_add_f32_e32 v108, v82, v108
	v_add_f32_e32 v108, v83, v108
	v_add_f32_e32 v108, v84, v108
	v_add_f32_e32 v108, v85, v108
	v_cvt_pk_bf16_f32 v156, v80, v81
	v_cvt_pk_bf16_f32 v157, v82, v83
	s_waitcnt lgkmcnt(0)
	v_mfma_f32_32x32x16_bf16 v[112:127], v[100:103], v[104:107], 0
	ds_read_b64_tr_b16 v[80:81], v188 offset:45056
	ds_read_b64_tr_b16 v[82:83], v188 offset:45568
	ds_read_b128 v[100:103], v168
	v_add_f32_e32 v104, v86, v108
	v_add_f32_e32 v104, v87, v104
	v_add_f32_e32 v104, v88, v104
	v_add_f32_e32 v144, v89, v104
	v_cvt_pk_bf16_f32 v158, v84, v85
	v_cvt_pk_bf16_f32 v159, v86, v87
	s_waitcnt lgkmcnt(0)
	v_mfma_f32_32x32x16_bf16 v[96:111], v[96:99], v[100:103], 0
	ds_read_b64_tr_b16 v[84:85], v188 offset:41984
	ds_read_b64_tr_b16 v[86:87], v188 offset:42496
	ds_read_b128 v[194:197], v168 offset:1024
	v_add_f32_e32 v144, v90, v144
	v_add_f32_e32 v144, v91, v144
	v_add_f32_e32 v144, v92, v144
	v_add_f32_e32 v144, v93, v144
	v_cvt_pk_bf16_f32 v152, v88, v89
	v_cvt_pk_bf16_f32 v153, v90, v91
	s_waitcnt lgkmcnt(0)
	v_mfma_f32_32x32x16_bf16 v[112:127], v[164:167], v[194:197], v[112:127]
	ds_read_b64_tr_b16 v[88:89], v188 offset:46080
	ds_read_b64_tr_b16 v[90:91], v188 offset:46592
	ds_read_b128 v[164:167], v168 offset:1024
	v_add_f32_e32 v144, v94, v144
	v_add_f32_e32 v144, v95, v144
	v_add_f32_e32 v144, v64, v144
	v_add_f32_e32 v144, v65, v144
	v_cvt_pk_bf16_f32 v154, v92, v93
	v_cvt_pk_bf16_f32 v155, v94, v95
	s_waitcnt lgkmcnt(0)
	v_mfma_f32_32x32x16_bf16 v[96:111], v[160:163], v[164:167], v[96:111]
	ds_read_b64_tr_b16 v[194:195], v188 offset:43008
	ds_read_b64_tr_b16 v[196:197], v188 offset:43520
	ds_read_b128 v[92:95], v168 offset:2048
	v_add_f32_e32 v144, v66, v144
	v_add_f32_e32 v144, v67, v144
	v_add_f32_e32 v144, v68, v144
	v_add_f32_e32 v144, v69, v144
	v_cvt_pk_bf16_f32 v148, v64, v65
	v_cvt_pk_bf16_f32 v149, v66, v67
	s_waitcnt lgkmcnt(0)
	v_mfma_f32_32x32x16_bf16 v[112:127], v[140:143], v[92:95], v[112:127]
	ds_read_b64_tr_b16 v[140:141], v188 offset:47104
	ds_read_b64_tr_b16 v[142:143], v188 offset:47616
	ds_read_b128 v[64:67], v168 offset:2048
	v_add_f32_e32 v92, v70, v144
	v_add_f32_e32 v92, v71, v92
	v_add_f32_e32 v92, v72, v92
	v_add_f32_e32 v92, v73, v92
	v_cvt_pk_bf16_f32 v150, v68, v69
	v_cvt_pk_bf16_f32 v151, v70, v71
	s_waitcnt lgkmcnt(0)
	v_mfma_f32_32x32x16_bf16 v[96:111], v[136:139], v[64:67], v[96:111]
	ds_read_b64_tr_b16 v[136:137], v188 offset:44032
	ds_read_b64_tr_b16 v[138:139], v188 offset:44544
	ds_read_b128 v[64:67], v168 offset:3072
	v_add_f32_e32 v68, v74, v92
	v_add_f32_e32 v68, v75, v68
	v_add_f32_e32 v68, v76, v68
	v_add_f32_e32 v68, v77, v68
	v_cvt_pk_bf16_f32 v144, v72, v73
	v_cvt_pk_bf16_f32 v145, v74, v75
	s_waitcnt lgkmcnt(0)
	v_mfma_f32_32x32x16_bf16 v[112:127], v[132:135], v[64:67], v[112:127]
	ds_read_b64_tr_b16 v[72:73], v188 offset:48128
	ds_read_b64_tr_b16 v[74:75], v188 offset:48640
	ds_read_b128 v[64:67], v168 offset:3072
	v_add_f32_e32 v68, v78, v68
	v_add_f32_e32 v68, v79, v68
	v_add_f32_e32 v68, 0, v68
	v_cvt_pk_bf16_f32 v146, v76, v77
	v_cvt_pk_bf16_f32 v147, v78, v79
	s_waitcnt lgkmcnt(0)
	v_mfma_f32_32x32x16_bf16 v[96:111], v[128:131], v[64:67], v[96:111]
	s_add_i32 s85, s85, s35
	v_lshl_add_u64 v[64:65], v[174:175], 0, s[60:61]
	s_add_i32 s35, s85, 0x4000
	s_mov_b32 s86, m0
	s_mov_b32 m0, s35
	s_nop 0
	global_load_lds_dwordx4 v[64:65], off
	s_mov_b32 m0, s86
	v_lshl_add_u64 v[64:65], v[170:171], 0, s[62:63]
	s_mov_b32 s35, m0
	s_mov_b32 m0, s16
	s_nop 0
	global_load_lds_dwordx4 v[64:65], off
	s_mov_b32 m0, s35
	v_lshl_add_u64 v[64:65], v[172:173], 0, s[62:63]
	s_add_i32 s35, s16, 0x2000
	s_mov_b32 s86, m0
	s_mov_b32 m0, s35
	s_nop 0
	global_load_lds_dwordx4 v[64:65], off
	s_mov_b32 m0, s86
	v_add_f32_e32 v198, v193, v68
	v_mfma_f32_32x32x16_bf16 v[48:63], v[156:159], v[178:181], v[48:63]
	ds_read_b64_tr_b16 v[76:77], v188 offset:49152
	ds_read_b64_tr_b16 v[78:79], v188 offset:49664
	v_exp_f32_e32 v112, v112
	v_exp_f32_e32 v113, v113
	v_mfma_f32_32x32x16_bf16 v[32:47], v[156:159], v[80:83], v[32:47]
	ds_read_b64_tr_b16 v[128:129], v188 offset:53248
	ds_read_b64_tr_b16 v[130:131], v188 offset:53760
	v_exp_f32_e32 v114, v114
	v_exp_f32_e32 v115, v115
	ds_read_b128 v[68:71], v234
	ds_read_b128 v[64:67], v234 offset:4096
	v_mfma_f32_32x32x16_bf16 v[48:63], v[152:155], v[84:87], v[48:63]
	ds_read_b64_tr_b16 v[132:133], v188 offset:50176
	ds_read_b64_tr_b16 v[134:135], v188 offset:50688
	v_exp_f32_e32 v116, v116
	v_exp_f32_e32 v117, v117
	ds_read_b128 v[164:167], v235
	ds_read_b128 v[92:95], v235 offset:4096
	v_mfma_f32_32x32x16_bf16 v[32:47], v[152:155], v[88:91], v[32:47]
	ds_read_b64_tr_b16 v[178:179], v188 offset:54272
	ds_read_b64_tr_b16 v[180:181], v188 offset:54784
	v_exp_f32_e32 v118, v118
	v_exp_f32_e32 v119, v119
	ds_read_b128 v[160:163], v236
	ds_read_b128 v[84:87], v236 offset:4096
	v_mfma_f32_32x32x16_bf16 v[48:63], v[148:151], v[194:197], v[48:63]
	ds_read_b64_tr_b16 v[190:191], v188 offset:51200
	ds_read_b64_tr_b16 v[192:193], v188 offset:51712
	v_exp_f32_e32 v120, v120
	v_exp_f32_e32 v121, v121
	ds_read_b128 v[88:91], v237
	ds_read_b128 v[80:83], v237 offset:4096
	v_mfma_f32_32x32x16_bf16 v[32:47], v[148:151], v[140:143], v[32:47]
	ds_read_b64_tr_b16 v[194:195], v188 offset:55296
	ds_read_b64_tr_b16 v[196:197], v188 offset:55808
	v_exp_f32_e32 v122, v122
	v_exp_f32_e32 v123, v123
	v_mfma_f32_32x32x16_bf16 v[48:63], v[144:147], v[136:139], v[48:63]
	ds_read_b64_tr_b16 v[140:141], v188 offset:52224
	ds_read_b64_tr_b16 v[142:143], v188 offset:52736
	v_exp_f32_e32 v124, v124
	v_exp_f32_e32 v125, v125
	v_mfma_f32_32x32x16_bf16 v[32:47], v[144:147], v[72:75], v[32:47]
	ds_read_b64_tr_b16 v[136:137], v188 offset:56320
	ds_read_b64_tr_b16 v[138:139], v188 offset:56832
	v_exp_f32_e32 v126, v126
	v_exp_f32_e32 v127, v127
	s_waitcnt lgkmcnt(14)
;   #define RESC() do{ if(!NOMAX&&resc){ asm volatile("s_waitcnt lgkmcnt(0)":::"memory"); \
;       _Pragma("unroll") for(int d_=0;d_<2*VM;++d_) _Pragma("unroll") for(int r=0;r<16;++r)o[d_][r]*=wsf[crow(r,hi)]; } }while(0)
;   #define ROT() do{sl_prev=sl_cur;sl_cur=sl_next;sl_next=(sl_next==(NSLOT-1)*SLOTB)?0:sl_next+SLOTB;}while(0)
;   #define ENDW(tt) do{ if((tt)+3<NT){ if constexpr(VM==2){WAIT_BAR(3);}else{WAIT_BAR(2);} } else if((tt)+2<NT){ if constexpr(VM==2){WAIT_BAR(2);}else{WAIT_BAR(1);} } else {WAIT_BAR(0);} }while(0)
; template<int THRL,int VM,bool NOMAX> __device__ __forceinline__ void attn_unit(const bf16*Qb,const bf16*__restrict__ Kh,const bf16*__restrict__ Vh,bf16*Ob,const int NT,const int sp,float*wscr,char*shm){
;     ...
;   for(;t+1<NT;t+=2){
;     STEP(pB0,pB1,pA0,pA1,t,(t+3<NT),(t+1<NT),(t+1<NT));       ENDW(t);   RESC(); ROT();
;     STEP(pA0,pA1,pB0,pB1,t+1,(t+4<NT),(t+2<NT),(t+2<NT));     ENDW(t+1); RESC(); ROT();
	v_mfma_f32_32x32x16_bf16 v[16:31], v[156:159], v[76:79], v[16:31]
	v_exp_f32_e32 v96, v96
	v_exp_f32_e32 v97, v97
	v_mfma_f32_32x32x16_bf16 v[0:15], v[156:159], v[128:131], v[0:15]
	v_exp_f32_e32 v98, v98
	v_exp_f32_e32 v99, v99
	v_mfma_f32_32x32x16_bf16 v[16:31], v[152:155], v[132:135], v[16:31]
	v_exp_f32_e32 v100, v100
	v_exp_f32_e32 v101, v101
	s_waitcnt lgkmcnt(12)
	v_mfma_f32_32x32x16_bf16 v[0:15], v[152:155], v[178:181], v[0:15]
	v_exp_f32_e32 v102, v102
	v_exp_f32_e32 v103, v103
	s_waitcnt lgkmcnt(8)
	v_mfma_f32_32x32x16_bf16 v[16:31], v[148:151], v[190:193], v[16:31]
	v_exp_f32_e32 v104, v104
	v_exp_f32_e32 v105, v105
	s_waitcnt lgkmcnt(4)
	v_mfma_f32_32x32x16_bf16 v[0:15], v[148:151], v[194:197], v[0:15]
	v_exp_f32_e32 v106, v106
	v_exp_f32_e32 v107, v107
	s_waitcnt lgkmcnt(2)
	v_mfma_f32_32x32x16_bf16 v[16:31], v[144:147], v[140:143], v[16:31]
	v_exp_f32_e32 v108, v108
	v_exp_f32_e32 v109, v109
	s_waitcnt lgkmcnt(0)
	v_mfma_f32_32x32x16_bf16 v[0:15], v[144:147], v[136:139], v[0:15]
	v_exp_f32_e32 v110, v110
	v_exp_f32_e32 v111, v111
	s_waitcnt vmcnt(3) lgkmcnt(0)
	s_barrier
	ds_read_b64_tr_b16 v[178:179], v188 offset:57344
	ds_read_b64_tr_b16 v[180:181], v188 offset:57856
	v_add_f32_e32 v76, v112, v113
	ds_read_b128 v[72:75], v168
	v_add_f32_e32 v76, v114, v76
	v_add_f32_e32 v76, v115, v76
	v_add_f32_e32 v76, v116, v76
	v_add_f32_e32 v76, v117, v76
	v_cvt_pk_bf16_f32 v156, v112, v113
	v_cvt_pk_bf16_f32 v157, v114, v115
	s_waitcnt lgkmcnt(0)
	v_mfma_f32_32x32x16_bf16 v[128:143], v[68:71], v[72:75], 0
	ds_read_b64_tr_b16 v[112:113], v188 offset:61440
	ds_read_b64_tr_b16 v[114:115], v188 offset:61952
	ds_read_b128 v[68:71], v168
	v_add_f32_e32 v72, v118, v76
	v_add_f32_e32 v72, v119, v72
	v_add_f32_e32 v72, v120, v72
	v_add_f32_e32 v144, v121, v72
	s_waitcnt lgkmcnt(0)
	v_mfma_f32_32x32x16_bf16 v[64:79], v[64:67], v[68:71], 0
	v_cvt_pk_bf16_f32 v158, v116, v117
	v_cvt_pk_bf16_f32 v159, v118, v119
	ds_read_b64_tr_b16 v[116:117], v188 offset:58368
	ds_read_b64_tr_b16 v[118:119], v188 offset:58880
	ds_read_b128 v[190:193], v168 offset:1024
	v_add_f32_e32 v144, v122, v144
	v_add_f32_e32 v144, v123, v144
	v_add_f32_e32 v144, v124, v144
	v_add_f32_e32 v144, v125, v144
	v_cvt_pk_bf16_f32 v152, v120, v121
	v_cvt_pk_bf16_f32 v153, v122, v123
	s_waitcnt lgkmcnt(0)
	v_mfma_f32_32x32x16_bf16 v[128:143], v[164:167], v[190:193], v[128:143]
	ds_read_b64_tr_b16 v[120:121], v188 offset:62464
	ds_read_b64_tr_b16 v[122:123], v188 offset:62976
	ds_read_b128 v[164:167], v168 offset:1024
	v_add_f32_e32 v144, v126, v144
	v_add_f32_e32 v144, v127, v144
	v_add_f32_e32 v144, v96, v144
	v_add_f32_e32 v144, v97, v144
	s_waitcnt lgkmcnt(0)
	v_mfma_f32_32x32x16_bf16 v[64:79], v[92:95], v[164:167], v[64:79]
	v_cvt_pk_bf16_f32 v154, v124, v125
	v_cvt_pk_bf16_f32 v155, v126, v127
	ds_read_b64_tr_b16 v[92:93], v188 offset:59392
	ds_read_b64_tr_b16 v[94:95], v188 offset:59904
	ds_read_b128 v[124:127], v168 offset:2048
	v_add_f32_e32 v144, v98, v144
	v_add_f32_e32 v144, v99, v144
	v_add_f32_e32 v144, v100, v144
	v_add_f32_e32 v144, v101, v144
	v_cvt_pk_bf16_f32 v148, v96, v97
	v_cvt_pk_bf16_f32 v149, v98, v99
	s_waitcnt lgkmcnt(0)
	v_mfma_f32_32x32x16_bf16 v[128:143], v[160:163], v[124:127], v[128:143]
	ds_read_b64_tr_b16 v[96:97], v188 offset:63488
	ds_read_b64_tr_b16 v[98:99], v188 offset:64000
	ds_read_b128 v[124:127], v168 offset:2048
	v_add_f32_e32 v144, v102, v144
	v_add_f32_e32 v144, v103, v144
	v_add_f32_e32 v144, v104, v144
	v_add_f32_e32 v144, v105, v144
	s_waitcnt lgkmcnt(0)
	v_mfma_f32_32x32x16_bf16 v[64:79], v[84:87], v[124:127], v[64:79]
	v_cvt_pk_bf16_f32 v150, v100, v101
	v_cvt_pk_bf16_f32 v151, v102, v103
	ds_read_b64_tr_b16 v[100:101], v188 offset:60416
	ds_read_b64_tr_b16 v[102:103], v188 offset:60928
	ds_read_b128 v[84:87], v168 offset:3072
	v_add_f32_e32 v124, v106, v144
	v_add_f32_e32 v124, v107, v124
	v_add_f32_e32 v124, v108, v124
	v_add_f32_e32 v124, v109, v124
	v_cvt_pk_bf16_f32 v144, v104, v105
	v_cvt_pk_bf16_f32 v145, v106, v107
	s_waitcnt lgkmcnt(0)
	v_mfma_f32_32x32x16_bf16 v[128:143], v[88:91], v[84:87], v[128:143]
	ds_read_b64_tr_b16 v[88:89], v188 offset:64512
	ds_read_b64_tr_b16 v[90:91], v188 offset:65024
	ds_read_b128 v[84:87], v168 offset:3072
	v_add_f32_e32 v104, v110, v124
	v_add_f32_e32 v104, v111, v104
	v_add_f32_e32 v104, 0, v104
	v_cvt_pk_bf16_f32 v146, v108, v109
	s_waitcnt lgkmcnt(0)
;   #define RESC() do{ if(!NOMAX&&resc){ asm volatile("s_waitcnt lgkmcnt(0)":::"memory"); \
;       _Pragma("unroll") for(int d_=0;d_<2*VM;++d_) _Pragma("unroll") for(int r=0;r<16;++r)o[d_][r]*=wsf[crow(r,hi)]; } }while(0)
;   #define ROT() do{sl_prev=sl_cur;sl_cur=sl_next;sl_next=(sl_next==(NSLOT-1)*SLOTB)?0:sl_next+SLOTB;}while(0)
;   #define ENDW(tt) do{ if((tt)+3<NT){ if constexpr(VM==2){WAIT_BAR(3);}else{WAIT_BAR(2);} } else if((tt)+2<NT){ if constexpr(VM==2){WAIT_BAR(2);}else{WAIT_BAR(1);} } else {WAIT_BAR(0);} }while(0)
; template<int THRL,int VM,bool NOMAX> __device__ __forceinline__ void attn_unit(const bf16*Qb,const bf16*__restrict__ Kh,const bf16*__restrict__ Vh,bf16*Ob,const int NT,const int sp,float*wscr,char*shm){
;     ...
;   for(;t+1<NT;t+=2){
;     STEP(pB0,pB1,pA0,pA1,t,(t+3<NT),(t+1<NT),(t+1<NT));       ENDW(t);   RESC(); ROT();
;     STEP(pA0,pA1,pB0,pB1,t+1,(t+4<NT),(t+2<NT),(t+2<NT));     ENDW(t+1); RESC(); ROT();
	v_mfma_f32_32x32x16_bf16 v[64:79], v[80:83], v[84:87], v[64:79]
	v_cvt_pk_bf16_f32 v147, v110, v111
	v_lshl_add_u64 v[80:81], v[174:175], 0, s[64:65]
	s_mov_b32 s86, m0
	s_mov_b32 m0, s17
	s_nop 0
	global_load_lds_dwordx4 v[80:81], off
	s_mov_b32 m0, s86
	v_lshl_add_u64 v[80:81], v[170:171], 0, s[66:67]
	s_add_i32 s17, s85, 0xa000
	s_mov_b32 s86, m0
	s_mov_b32 m0, s17
	s_nop 0
	global_load_lds_dwordx4 v[80:81], off
	s_mov_b32 m0, s86
	v_lshl_add_u64 v[80:81], v[172:173], 0, s[66:67]
	s_add_i32 s17, s85, 0xc000
	s_mov_b32 s86, m0
	s_mov_b32 m0, s17
	s_nop 0
	global_load_lds_dwordx4 v[80:81], off
	s_mov_b32 m0, s86
	v_add_f32_e32 v198, v198, v104
	v_mfma_f32_32x32x16_bf16 v[48:63], v[156:159], v[178:181], v[48:63]
	ds_read_b64_tr_b16 v[104:105], v177 offset:40960
	ds_read_b64_tr_b16 v[106:107], v177 offset:41472
	v_exp_f32_e32 v128, v128
	v_exp_f32_e32 v129, v129
	v_mfma_f32_32x32x16_bf16 v[32:47], v[156:159], v[112:115], v[32:47]
	ds_read_b64_tr_b16 v[108:109], v177 offset:45056
	ds_read_b64_tr_b16 v[110:111], v177 offset:45568
	v_exp_f32_e32 v130, v130
	v_exp_f32_e32 v131, v131
	ds_read_b128 v[84:87], v234 offset:8192
	ds_read_b128 v[80:83], v234 offset:12288
	v_mfma_f32_32x32x16_bf16 v[48:63], v[152:155], v[116:119], v[48:63]
	ds_read_b64_tr_b16 v[178:179], v177 offset:41984
	ds_read_b64_tr_b16 v[180:181], v177 offset:42496
	v_exp_f32_e32 v132, v132
	v_exp_f32_e32 v133, v133
	ds_read_b128 v[164:167], v235 offset:8192
	ds_read_b128 v[124:127], v235 offset:12288
	v_mfma_f32_32x32x16_bf16 v[32:47], v[152:155], v[120:123], v[32:47]
	ds_read_b64_tr_b16 v[190:191], v177 offset:46080
	ds_read_b64_tr_b16 v[192:193], v177 offset:46592
	v_exp_f32_e32 v134, v134
	v_exp_f32_e32 v135, v135
	ds_read_b128 v[160:163], v236 offset:8192
	ds_read_b128 v[116:119], v236 offset:12288
	v_mfma_f32_32x32x16_bf16 v[48:63], v[148:151], v[92:95], v[48:63]
	ds_read_b64_tr_b16 v[194:195], v177 offset:43008
	ds_read_b64_tr_b16 v[196:197], v177 offset:43520
	v_exp_f32_e32 v136, v136
	v_exp_f32_e32 v137, v137
	ds_read_b128 v[120:123], v237 offset:8192
	ds_read_b128 v[112:115], v237 offset:12288
	v_mfma_f32_32x32x16_bf16 v[32:47], v[148:151], v[96:99], v[32:47]
	ds_read_b64_tr_b16 v[92:93], v177 offset:47104
	ds_read_b64_tr_b16 v[94:95], v177 offset:47616
	v_exp_f32_e32 v138, v138
	v_exp_f32_e32 v139, v139
	v_mfma_f32_32x32x16_bf16 v[48:63], v[144:147], v[100:103], v[48:63]
	ds_read_b64_tr_b16 v[96:97], v177 offset:44032
	ds_read_b64_tr_b16 v[98:99], v177 offset:44544
	v_exp_f32_e32 v140, v140
	v_exp_f32_e32 v141, v141
	v_mfma_f32_32x32x16_bf16 v[32:47], v[144:147], v[88:91], v[32:47]
	ds_read_b64_tr_b16 v[100:101], v177 offset:48128
	ds_read_b64_tr_b16 v[102:103], v177 offset:48640
	v_exp_f32_e32 v142, v142
	v_exp_f32_e32 v143, v143
	s_waitcnt lgkmcnt(14)
	v_mfma_f32_32x32x16_bf16 v[16:31], v[156:159], v[104:107], v[16:31]
	v_exp_f32_e32 v64, v64
	v_exp_f32_e32 v65, v65
	v_mfma_f32_32x32x16_bf16 v[0:15], v[156:159], v[108:111], v[0:15]
	v_exp_f32_e32 v66, v66
	v_exp_f32_e32 v67, v67
	v_mfma_f32_32x32x16_bf16 v[16:31], v[152:155], v[178:181], v[16:31]
	v_exp_f32_e32 v68, v68
	v_exp_f32_e32 v69, v69
	s_waitcnt lgkmcnt(12)
	v_mfma_f32_32x32x16_bf16 v[0:15], v[152:155], v[190:193], v[0:15]
	v_exp_f32_e32 v70, v70
	v_exp_f32_e32 v71, v71
	s_waitcnt lgkmcnt(8)
	v_mfma_f32_32x32x16_bf16 v[16:31], v[148:151], v[194:197], v[16:31]
	v_exp_f32_e32 v72, v72
	v_exp_f32_e32 v73, v73
	s_waitcnt lgkmcnt(4)
	v_mfma_f32_32x32x16_bf16 v[0:15], v[148:151], v[92:95], v[0:15]
	v_exp_f32_e32 v74, v74
	v_exp_f32_e32 v75, v75
	s_waitcnt lgkmcnt(2)
	v_mfma_f32_32x32x16_bf16 v[16:31], v[144:147], v[96:99], v[16:31]
	v_exp_f32_e32 v76, v76
	v_exp_f32_e32 v77, v77
	s_waitcnt lgkmcnt(0)
	v_mfma_f32_32x32x16_bf16 v[0:15], v[144:147], v[100:103], v[0:15]
	v_exp_f32_e32 v78, v78
	v_exp_f32_e32 v79, v79
	s_waitcnt vmcnt(3) lgkmcnt(0)
	s_barrier
	ds_read_b64_tr_b16 v[178:179], v188 offset:24576
	ds_read_b64_tr_b16 v[180:181], v188 offset:25088
	v_add_f32_e32 v92, v128, v129
	ds_read_b128 v[88:91], v168
	v_add_f32_e32 v92, v130, v92
	v_add_f32_e32 v92, v131, v92
	v_add_f32_e32 v92, v132, v92
	v_add_f32_e32 v92, v133, v92
	v_cvt_pk_bf16_f32 v156, v128, v129
	v_cvt_pk_bf16_f32 v157, v130, v131
	s_waitcnt lgkmcnt(0)
	v_mfma_f32_32x32x16_bf16 v[96:111], v[84:87], v[88:91], 0
	ds_read_b64_tr_b16 v[128:129], v188 offset:28672
	ds_read_b64_tr_b16 v[130:131], v188 offset:29184
	ds_read_b128 v[84:87], v168
	v_add_f32_e32 v88, v134, v92
	v_add_f32_e32 v88, v135, v88
	v_add_f32_e32 v88, v136, v88
	v_add_f32_e32 v144, v137, v88
	v_cvt_pk_bf16_f32 v158, v132, v133
	v_cvt_pk_bf16_f32 v159, v134, v135
	s_waitcnt lgkmcnt(0)
	v_mfma_f32_32x32x16_bf16 v[80:95], v[80:83], v[84:87], 0
	ds_read_b64_tr_b16 v[132:133], v188 offset:25600
	ds_read_b64_tr_b16 v[134:135], v188 offset:26112
	ds_read_b128 v[190:193], v168 offset:1024
	v_add_f32_e32 v144, v138, v144
	v_add_f32_e32 v144, v139, v144
	v_add_f32_e32 v144, v140, v144
	v_add_f32_e32 v144, v141, v144
	v_cvt_pk_bf16_f32 v152, v136, v137
	v_cvt_pk_bf16_f32 v153, v138, v139
	s_waitcnt lgkmcnt(0)
	v_mfma_f32_32x32x16_bf16 v[96:111], v[164:167], v[190:193], v[96:111]
	ds_read_b64_tr_b16 v[136:137], v188 offset:29696
	ds_read_b64_tr_b16 v[138:139], v188 offset:30208
	ds_read_b128 v[164:167], v168 offset:1024
	v_add_f32_e32 v144, v142, v144
	v_add_f32_e32 v144, v143, v144
	v_add_f32_e32 v144, v64, v144
	v_add_f32_e32 v144, v65, v144
	v_cvt_pk_bf16_f32 v154, v140, v141
	v_cvt_pk_bf16_f32 v155, v142, v143
	s_waitcnt lgkmcnt(0)
;   #define RESC() do{ if(!NOMAX&&resc){ asm volatile("s_waitcnt lgkmcnt(0)":::"memory"); \
;       _Pragma("unroll") for(int d_=0;d_<2*VM;++d_) _Pragma("unroll") for(int r=0;r<16;++r)o[d_][r]*=wsf[crow(r,hi)]; } }while(0)
;   #define ROT() do{sl_prev=sl_cur;sl_cur=sl_next;sl_next=(sl_next==(NSLOT-1)*SLOTB)?0:sl_next+SLOTB;}while(0)
;   #define ENDW(tt) do{ if((tt)+3<NT){ if constexpr(VM==2){WAIT_BAR(3);}else{WAIT_BAR(2);} } else if((tt)+2<NT){ if constexpr(VM==2){WAIT_BAR(2);}else{WAIT_BAR(1);} } else {WAIT_BAR(0);} }while(0)
; template<int THRL,int VM,bool NOMAX> __device__ __forceinline__ void attn_unit(const bf16*Qb,const bf16*__restrict__ Kh,const bf16*__restrict__ Vh,bf16*Ob,const int NT,const int sp,float*wscr,char*shm){
;     ...
;   for(;t+1<NT;t+=2){
;     STEP(pB0,pB1,pA0,pA1,t,(t+3<NT),(t+1<NT),(t+1<NT));       ENDW(t);   RESC(); ROT();
;     STEP(pA0,pA1,pB0,pB1,t+1,(t+4<NT),(t+2<NT),(t+2<NT));     ENDW(t+1); RESC(); ROT();
	v_mfma_f32_32x32x16_bf16 v[80:95], v[124:127], v[164:167], v[80:95]
	ds_read_b64_tr_b16 v[124:125], v188 offset:26624
	ds_read_b64_tr_b16 v[126:127], v188 offset:27136
	ds_read_b128 v[140:143], v168 offset:2048
	v_add_f32_e32 v144, v66, v144
	v_add_f32_e32 v144, v67, v144
	v_add_f32_e32 v144, v68, v144
	v_add_f32_e32 v144, v69, v144
	v_cvt_pk_bf16_f32 v148, v64, v65
	v_cvt_pk_bf16_f32 v149, v66, v67
	s_waitcnt lgkmcnt(0)
	v_mfma_f32_32x32x16_bf16 v[96:111], v[160:163], v[140:143], v[96:111]
	ds_read_b64_tr_b16 v[190:191], v188 offset:30720
	ds_read_b64_tr_b16 v[192:193], v188 offset:31232
	ds_read_b128 v[64:67], v168 offset:2048
	v_add_f32_e32 v140, v70, v144
	v_add_f32_e32 v140, v71, v140
	v_add_f32_e32 v140, v72, v140
	v_add_f32_e32 v140, v73, v140
	v_cvt_pk_bf16_f32 v150, v68, v69
	v_cvt_pk_bf16_f32 v151, v70, v71
	s_waitcnt lgkmcnt(0)
	v_mfma_f32_32x32x16_bf16 v[80:95], v[116:119], v[64:67], v[80:95]
	ds_read_b64_tr_b16 v[116:117], v188 offset:27648
	ds_read_b64_tr_b16 v[118:119], v188 offset:28160
	ds_read_b128 v[64:67], v168 offset:3072
	v_add_f32_e32 v68, v74, v140
	v_add_f32_e32 v68, v75, v68
	v_add_f32_e32 v68, v76, v68
	v_add_f32_e32 v68, v77, v68
	v_cvt_pk_bf16_f32 v144, v72, v73
	v_cvt_pk_bf16_f32 v145, v74, v75
	s_waitcnt lgkmcnt(0)
	v_mfma_f32_32x32x16_bf16 v[96:111], v[120:123], v[64:67], v[96:111]
	ds_read_b64_tr_b16 v[72:73], v188 offset:31744
	ds_read_b64_tr_b16 v[74:75], v188 offset:32256
	ds_read_b128 v[64:67], v168 offset:3072
	v_add_f32_e32 v68, v78, v68
	v_add_f32_e32 v68, v79, v68
	v_add_f32_e32 v68, 0, v68
	v_cvt_pk_bf16_f32 v146, v76, v77
	v_cvt_pk_bf16_f32 v147, v78, v79
	s_waitcnt lgkmcnt(0)
	v_mfma_f32_32x32x16_bf16 v[80:95], v[112:115], v[64:67], v[80:95]
	v_lshl_add_u64 v[64:65], v[170:171], 0, s[60:61]
	s_add_i32 s17, s85, 0xe000
	s_mov_b32 s86, m0
	s_mov_b32 m0, s17
	s_nop 0
	global_load_lds_dwordx4 v[64:65], off
	s_mov_b32 m0, s86
	v_lshl_add_u64 v[64:65], v[172:173], 0, s[60:61]
	s_add_i32 s85, s85, 0x10000
	s_mov_b32 s17, m0
	s_mov_b32 m0, s85
	s_nop 0
	global_load_lds_dwordx4 v[64:65], off
	s_mov_b32 m0, s17
	v_add_f32_e32 v174, v198, v68
	v_mfma_f32_32x32x16_bf16 v[48:63], v[156:159], v[178:181], v[48:63]
	ds_read_b64_tr_b16 v[76:77], v188 offset:32768
	ds_read_b64_tr_b16 v[78:79], v188 offset:33280
	v_exp_f32_e32 v96, v96
	v_exp_f32_e32 v97, v97
	v_mfma_f32_32x32x16_bf16 v[32:47], v[156:159], v[128:131], v[32:47]
	ds_read_b64_tr_b16 v[112:113], v188 offset:36864
	ds_read_b64_tr_b16 v[114:115], v188 offset:37376
	v_exp_f32_e32 v98, v98
	v_exp_f32_e32 v99, v99
	ds_read_b128 v[68:71], v234 offset:16384
	ds_read_b128 v[64:67], v234 offset:20480
	v_mfma_f32_32x32x16_bf16 v[48:63], v[152:155], v[132:135], v[48:63]
	ds_read_b64_tr_b16 v[120:121], v188 offset:33792
	ds_read_b64_tr_b16 v[122:123], v188 offset:34304
	v_exp_f32_e32 v100, v100
	v_exp_f32_e32 v101, v101
	ds_read_b128 v[164:167], v235 offset:16384
	ds_read_b128 v[140:143], v235 offset:20480
	v_mfma_f32_32x32x16_bf16 v[32:47], v[152:155], v[136:139], v[32:47]
	ds_read_b64_tr_b16 v[178:179], v188 offset:37888
	ds_read_b64_tr_b16 v[180:181], v188 offset:38400
	v_exp_f32_e32 v102, v102
	v_exp_f32_e32 v103, v103
	ds_read_b128 v[160:163], v236 offset:16384
	ds_read_b128 v[132:135], v236 offset:20480
	v_mfma_f32_32x32x16_bf16 v[48:63], v[148:151], v[124:127], v[48:63]
	ds_read_b64_tr_b16 v[194:195], v188 offset:34816
	ds_read_b64_tr_b16 v[196:197], v188 offset:35328
	v_exp_f32_e32 v104, v104
	v_exp_f32_e32 v105, v105
	ds_read_b128 v[136:139], v237 offset:16384
	ds_read_b128 v[128:131], v237 offset:20480
	v_mfma_f32_32x32x16_bf16 v[32:47], v[148:151], v[190:193], v[32:47]
	ds_read_b64_tr_b16 v[124:125], v188 offset:38912
	ds_read_b64_tr_b16 v[126:127], v188 offset:39424
	v_exp_f32_e32 v106, v106
	v_exp_f32_e32 v107, v107
	v_mfma_f32_32x32x16_bf16 v[48:63], v[144:147], v[116:119], v[48:63]
	ds_read_b64_tr_b16 v[190:191], v188 offset:35840
	ds_read_b64_tr_b16 v[192:193], v188 offset:36352
	v_exp_f32_e32 v108, v108
	v_exp_f32_e32 v109, v109
	v_mfma_f32_32x32x16_bf16 v[32:47], v[144:147], v[72:75], v[32:47]
	ds_read_b64_tr_b16 v[116:117], v188 offset:39936
	ds_read_b64_tr_b16 v[118:119], v188 offset:40448
	v_exp_f32_e32 v110, v110
	v_exp_f32_e32 v111, v111
	s_waitcnt lgkmcnt(14)
	v_mfma_f32_32x32x16_bf16 v[16:31], v[156:159], v[76:79], v[16:31]
	v_exp_f32_e32 v80, v80
	v_exp_f32_e32 v81, v81
	v_mfma_f32_32x32x16_bf16 v[0:15], v[156:159], v[112:115], v[0:15]
	v_exp_f32_e32 v82, v82
	v_exp_f32_e32 v83, v83
	v_mfma_f32_32x32x16_bf16 v[16:31], v[152:155], v[120:123], v[16:31]
	v_exp_f32_e32 v84, v84
	v_exp_f32_e32 v85, v85
	s_waitcnt lgkmcnt(12)
	v_mfma_f32_32x32x16_bf16 v[0:15], v[152:155], v[178:181], v[0:15]
	v_exp_f32_e32 v86, v86
	v_exp_f32_e32 v87, v87
	s_waitcnt lgkmcnt(8)
	v_mfma_f32_32x32x16_bf16 v[16:31], v[148:151], v[194:197], v[16:31]
	v_exp_f32_e32 v88, v88
	v_exp_f32_e32 v89, v89
	s_waitcnt lgkmcnt(4)
	v_mfma_f32_32x32x16_bf16 v[0:15], v[148:151], v[124:127], v[0:15]
	v_exp_f32_e32 v90, v90
	v_exp_f32_e32 v91, v91
	s_waitcnt lgkmcnt(2)
	v_mfma_f32_32x32x16_bf16 v[16:31], v[144:147], v[190:193], v[16:31]
	v_exp_f32_e32 v92, v92
	v_exp_f32_e32 v93, v93
	s_waitcnt lgkmcnt(0)
	v_mfma_f32_32x32x16_bf16 v[0:15], v[144:147], v[116:119], v[0:15]
	v_exp_f32_e32 v94, v94
	v_exp_f32_e32 v95, v95
	s_waitcnt vmcnt(2) lgkmcnt(0)
	s_barrier
;   #define RESC() do{ if(!NOMAX&&resc){ asm volatile("s_waitcnt lgkmcnt(0)":::"memory"); \
;       _Pragma("unroll") for(int d_=0;d_<2*VM;++d_) _Pragma("unroll") for(int r=0;r<16;++r)o[d_][r]*=wsf[crow(r,hi)]; } }while(0)
;   #define ROT() do{sl_prev=sl_cur;sl_cur=sl_next;sl_next=(sl_next==(NSLOT-1)*SLOTB)?0:sl_next+SLOTB;}while(0)
;   #define ENDW(tt) do{ if((tt)+3<NT){ if constexpr(VM==2){WAIT_BAR(3);}else{WAIT_BAR(2);} } else if((tt)+2<NT){ if constexpr(VM==2){WAIT_BAR(2);}else{WAIT_BAR(1);} } else {WAIT_BAR(0);} }while(0)
; template<int THRL,int VM,bool NOMAX> __device__ __forceinline__ void attn_unit(const bf16*Qb,const bf16*__restrict__ Kh,const bf16*__restrict__ Vh,bf16*Ob,const int NT,const int sp,float*wscr,char*shm){
;     ...
;   for(;t+1<NT;t+=2){
;     STEP(pB0,pB1,pA0,pA1,t,(t+3<NT),(t+1<NT),(t+1<NT));       ENDW(t);   RESC(); ROT();
;     STEP(pA0,pA1,pB0,pB1,t+1,(t+4<NT),(t+2<NT),(t+2<NT));     ENDW(t+1); RESC(); ROT();
	ds_read_b64_tr_b16 v[178:179], v188 offset:40960
	ds_read_b64_tr_b16 v[180:181], v188 offset:41472
	v_add_f32_e32 v76, v96, v97
	ds_read_b128 v[72:75], v168
	v_add_f32_e32 v76, v98, v76
	v_add_f32_e32 v76, v99, v76
	v_add_f32_e32 v76, v100, v76
	v_add_f32_e32 v76, v101, v76
	v_cvt_pk_bf16_f32 v156, v96, v97
	v_cvt_pk_bf16_f32 v157, v98, v99
	s_waitcnt lgkmcnt(0)
	v_mfma_f32_32x32x16_bf16 v[112:127], v[68:71], v[72:75], 0
	ds_read_b64_tr_b16 v[96:97], v188 offset:45056
	ds_read_b64_tr_b16 v[98:99], v188 offset:45568
	ds_read_b128 v[68:71], v168
	v_add_f32_e32 v72, v102, v76
	v_add_f32_e32 v72, v103, v72
	v_add_f32_e32 v72, v104, v72
	v_add_f32_e32 v144, v105, v72
	s_waitcnt lgkmcnt(0)
	v_mfma_f32_32x32x16_bf16 v[64:79], v[64:67], v[68:71], 0
	v_cvt_pk_bf16_f32 v158, v100, v101
	v_cvt_pk_bf16_f32 v159, v102, v103
	ds_read_b64_tr_b16 v[100:101], v188 offset:41984
	ds_read_b64_tr_b16 v[102:103], v188 offset:42496
	ds_read_b128 v[190:193], v168 offset:1024
	v_add_f32_e32 v144, v106, v144
	v_add_f32_e32 v144, v107, v144
	v_add_f32_e32 v144, v108, v144
	v_add_f32_e32 v144, v109, v144
	v_cvt_pk_bf16_f32 v152, v104, v105
	v_cvt_pk_bf16_f32 v153, v106, v107
	s_waitcnt lgkmcnt(0)
	v_mfma_f32_32x32x16_bf16 v[112:127], v[164:167], v[190:193], v[112:127]
	ds_read_b64_tr_b16 v[104:105], v188 offset:46080
	ds_read_b64_tr_b16 v[106:107], v188 offset:46592
	ds_read_b128 v[164:167], v168 offset:1024
	v_add_f32_e32 v144, v110, v144
	v_add_f32_e32 v144, v111, v144
	v_add_f32_e32 v144, v80, v144
	v_add_f32_e32 v144, v81, v144
	s_waitcnt lgkmcnt(0)
	v_mfma_f32_32x32x16_bf16 v[64:79], v[140:143], v[164:167], v[64:79]
	v_cvt_pk_bf16_f32 v154, v108, v109
	v_cvt_pk_bf16_f32 v155, v110, v111
	ds_read_b64_tr_b16 v[108:109], v188 offset:43008
	ds_read_b64_tr_b16 v[110:111], v188 offset:43520
	ds_read_b128 v[140:143], v168 offset:2048
	v_add_f32_e32 v144, v82, v144
	v_add_f32_e32 v144, v83, v144
	v_add_f32_e32 v144, v84, v144
	v_add_f32_e32 v144, v85, v144
	v_cvt_pk_bf16_f32 v148, v80, v81
	v_cvt_pk_bf16_f32 v149, v82, v83
	s_waitcnt lgkmcnt(0)
	v_mfma_f32_32x32x16_bf16 v[112:127], v[160:163], v[140:143], v[112:127]
	ds_read_b64_tr_b16 v[190:191], v188 offset:47104
	ds_read_b64_tr_b16 v[192:193], v188 offset:47616
	ds_read_b128 v[80:83], v168 offset:2048
	v_add_f32_e32 v140, v86, v144
	v_add_f32_e32 v140, v87, v140
	v_add_f32_e32 v140, v88, v140
	v_add_f32_e32 v140, v89, v140
	s_waitcnt lgkmcnt(0)
	v_mfma_f32_32x32x16_bf16 v[64:79], v[132:135], v[80:83], v[64:79]
	v_cvt_pk_bf16_f32 v150, v84, v85
	v_cvt_pk_bf16_f32 v151, v86, v87
	ds_read_b64_tr_b16 v[84:85], v188 offset:44032
	ds_read_b64_tr_b16 v[86:87], v188 offset:44544
	ds_read_b128 v[80:83], v168 offset:3072
	v_add_f32_e32 v132, v90, v140
	v_add_f32_e32 v132, v91, v132
	v_add_f32_e32 v132, v92, v132
	v_add_f32_e32 v132, v93, v132
	v_cvt_pk_bf16_f32 v144, v88, v89
	v_cvt_pk_bf16_f32 v145, v90, v91
	s_waitcnt lgkmcnt(0)
	v_mfma_f32_32x32x16_bf16 v[112:127], v[136:139], v[80:83], v[112:127]
	ds_read_b64_tr_b16 v[88:89], v188 offset:48128
	ds_read_b64_tr_b16 v[90:91], v188 offset:48640
	ds_read_b128 v[80:83], v168 offset:3072
	v_add_f32_e32 v132, v94, v132
	v_add_f32_e32 v132, v95, v132
	v_add_f32_e32 v132, 0, v132
	v_cvt_pk_bf16_f32 v146, v92, v93
	s_waitcnt lgkmcnt(0)
	v_mfma_f32_32x32x16_bf16 v[64:79], v[128:131], v[80:83], v[64:79]
	v_cvt_pk_bf16_f32 v147, v94, v95
	v_lshl_add_u64 v[80:81], v[170:171], 0, s[64:65]
	s_mov_b32 s17, m0
	s_mov_b32 m0, s16
	s_nop 0
	global_load_lds_dwordx4 v[80:81], off
	s_mov_b32 m0, s17
	v_lshl_add_u64 v[80:81], v[172:173], 0, s[64:65]
	s_mov_b32 s16, m0
	s_mov_b32 m0, s35
	s_nop 0
	global_load_lds_dwordx4 v[80:81], off
	s_mov_b32 m0, s16
	v_add_f32_e32 v174, v174, v132
	v_mfma_f32_32x32x16_bf16 v[48:63], v[156:159], v[178:181], v[48:63]
	ds_read_b64_tr_b16 v[92:93], v188 offset:49152
	ds_read_b64_tr_b16 v[94:95], v188 offset:49664
	v_exp_f32_e32 v112, v112
	v_exp_f32_e32 v113, v113
	v_mfma_f32_32x32x16_bf16 v[32:47], v[156:159], v[96:99], v[32:47]
	ds_read_b64_tr_b16 v[170:171], v188 offset:53248
	ds_read_b64_tr_b16 v[172:173], v188 offset:53760
	v_exp_f32_e32 v114, v114
	v_exp_f32_e32 v115, v115
	ds_read_b128 v[80:83], v234
	ds_read_b128 v[96:99], v234 offset:4096
	v_mfma_f32_32x32x16_bf16 v[48:63], v[152:155], v[100:103], v[48:63]
	ds_read_b64_tr_b16 v[178:179], v188 offset:50176
	ds_read_b64_tr_b16 v[180:181], v188 offset:50688
	v_exp_f32_e32 v116, v116
	v_exp_f32_e32 v117, v117
	ds_read_b128 v[164:167], v235
	ds_read_b128 v[140:143], v235 offset:4096
	v_mfma_f32_32x32x16_bf16 v[32:47], v[152:155], v[104:107], v[32:47]
	ds_read_b64_tr_b16 v[100:101], v188 offset:54272
	ds_read_b64_tr_b16 v[102:103], v188 offset:54784
	v_exp_f32_e32 v118, v118
	v_exp_f32_e32 v119, v119
	ds_read_b128 v[160:163], v236
	ds_read_b128 v[132:135], v236 offset:4096
	v_mfma_f32_32x32x16_bf16 v[48:63], v[148:151], v[108:111], v[48:63]
	ds_read_b64_tr_b16 v[104:105], v188 offset:51200
	ds_read_b64_tr_b16 v[106:107], v188 offset:51712
	v_exp_f32_e32 v120, v120
	v_exp_f32_e32 v121, v121
	ds_read_b128 v[136:139], v237
	ds_read_b128 v[128:131], v237 offset:4096
	v_mfma_f32_32x32x16_bf16 v[32:47], v[148:151], v[190:193], v[32:47]
	ds_read_b64_tr_b16 v[108:109], v188 offset:55296
	ds_read_b64_tr_b16 v[110:111], v188 offset:55808
	v_exp_f32_e32 v122, v122
	v_exp_f32_e32 v123, v123
	v_mfma_f32_32x32x16_bf16 v[48:63], v[144:147], v[84:87], v[48:63]
	ds_read_b64_tr_b16 v[190:191], v188 offset:52224
	ds_read_b64_tr_b16 v[192:193], v188 offset:52736
	v_exp_f32_e32 v124, v124
	v_exp_f32_e32 v125, v125
	v_mfma_f32_32x32x16_bf16 v[32:47], v[144:147], v[88:91], v[32:47]
	ds_read_b64_tr_b16 v[84:85], v188 offset:56320
	ds_read_b64_tr_b16 v[86:87], v188 offset:56832
	v_exp_f32_e32 v126, v126
	v_exp_f32_e32 v127, v127
	s_waitcnt lgkmcnt(14)
	v_mfma_f32_32x32x16_bf16 v[16:31], v[156:159], v[92:95], v[16:31]
	v_exp_f32_e32 v64, v64
	v_exp_f32_e32 v65, v65
	v_mfma_f32_32x32x16_bf16 v[0:15], v[156:159], v[170:173], v[0:15]
	v_exp_f32_e32 v66, v66
	v_exp_f32_e32 v67, v67
	v_mfma_f32_32x32x16_bf16 v[16:31], v[152:155], v[178:181], v[16:31]
	v_exp_f32_e32 v68, v68
	v_exp_f32_e32 v69, v69
	s_waitcnt lgkmcnt(12)
	v_mfma_f32_32x32x16_bf16 v[0:15], v[152:155], v[100:103], v[0:15]
	v_exp_f32_e32 v70, v70
	v_exp_f32_e32 v71, v71
	s_waitcnt lgkmcnt(8)
	v_mfma_f32_32x32x16_bf16 v[16:31], v[148:151], v[104:107], v[16:31]
	v_exp_f32_e32 v72, v72
	v_exp_f32_e32 v73, v73
	s_waitcnt lgkmcnt(4)
	v_mfma_f32_32x32x16_bf16 v[0:15], v[148:151], v[108:111], v[0:15]
	v_exp_f32_e32 v74, v74
	v_exp_f32_e32 v75, v75
	s_waitcnt lgkmcnt(2)
	v_mfma_f32_32x32x16_bf16 v[16:31], v[144:147], v[190:193], v[16:31]
	v_exp_f32_e32 v76, v76
	v_exp_f32_e32 v77, v77
	s_waitcnt lgkmcnt(0)
	v_mfma_f32_32x32x16_bf16 v[0:15], v[144:147], v[84:87], v[0:15]
	v_exp_f32_e32 v78, v78
	v_exp_f32_e32 v79, v79
	s_waitcnt vmcnt(0) lgkmcnt(0)
	s_barrier
;   #define RESC() do{ if(!NOMAX&&resc){ asm volatile("s_waitcnt lgkmcnt(0)":::"memory"); \
;       _Pragma("unroll") for(int d_=0;d_<2*VM;++d_) _Pragma("unroll") for(int r=0;r<16;++r)o[d_][r]*=wsf[crow(r,hi)]; } }while(0)
; template<int THRL,int VM,bool NOMAX> __device__ __forceinline__ void attn_unit(const bf16*Qb,const bf16*__restrict__ Kh,const bf16*__restrict__ Vh,bf16*Ob,const int NT,const int sp,float*wscr,char*shm){
;     ...
;   STEP(pB0,pB1,pA0,pA1,NT-1,false,false,false); RESC();
	ds_read_b64_tr_b16 v[170:171], v188 offset:57344
	ds_read_b64_tr_b16 v[172:173], v188 offset:57856
	v_add_f32_e32 v88, v112, v113
	ds_read_b128 v[84:87], v168
	v_add_f32_e32 v88, v114, v88
	v_add_f32_e32 v88, v115, v88
	v_add_f32_e32 v88, v116, v88
	v_add_f32_e32 v104, v117, v88
	v_cvt_pk_bf16_f32 v156, v112, v113
	v_cvt_pk_bf16_f32 v157, v114, v115
	s_waitcnt lgkmcnt(0)
	v_mfma_f32_32x32x16_bf16 v[80:95], v[80:83], v[84:87], 0
	ds_read_b64_tr_b16 v[112:113], v188 offset:61440
	ds_read_b64_tr_b16 v[114:115], v188 offset:61952
	ds_read_b128 v[100:103], v168
	v_add_f32_e32 v104, v118, v104
	v_add_f32_e32 v104, v119, v104
	v_add_f32_e32 v104, v120, v104
	v_add_f32_e32 v144, v121, v104
	v_cvt_pk_bf16_f32 v158, v116, v117
	v_cvt_pk_bf16_f32 v159, v118, v119
	s_waitcnt lgkmcnt(0)
	v_mfma_f32_32x32x16_bf16 v[96:111], v[96:99], v[100:103], 0
	ds_read_b64_tr_b16 v[116:117], v188 offset:58368
	ds_read_b64_tr_b16 v[118:119], v188 offset:58880
	ds_read_b128 v[178:181], v168 offset:1024
	v_add_f32_e32 v144, v122, v144
	v_add_f32_e32 v144, v123, v144
	v_add_f32_e32 v144, v124, v144
	v_add_f32_e32 v144, v125, v144
	v_cvt_pk_bf16_f32 v152, v120, v121
	v_cvt_pk_bf16_f32 v153, v122, v123
	s_waitcnt lgkmcnt(0)
	v_mfma_f32_32x32x16_bf16 v[80:95], v[164:167], v[178:181], v[80:95]
	ds_read_b64_tr_b16 v[120:121], v188 offset:62464
	ds_read_b64_tr_b16 v[122:123], v188 offset:62976
	ds_read_b128 v[164:167], v168 offset:1024
	v_add_f32_e32 v144, v126, v144
	v_add_f32_e32 v144, v127, v144
	v_add_f32_e32 v144, v64, v144
	v_add_f32_e32 v144, v65, v144
	v_cvt_pk_bf16_f32 v154, v124, v125
	v_cvt_pk_bf16_f32 v155, v126, v127
	s_waitcnt lgkmcnt(0)
	v_mfma_f32_32x32x16_bf16 v[96:111], v[140:143], v[164:167], v[96:111]
	ds_read_b64_tr_b16 v[124:125], v188 offset:59392
	ds_read_b64_tr_b16 v[126:127], v188 offset:59904
	ds_read_b128 v[140:143], v168 offset:2048
	v_add_f32_e32 v144, v66, v144
	v_add_f32_e32 v144, v67, v144
	v_add_f32_e32 v144, v68, v144
	v_add_f32_e32 v144, v69, v144
	v_cvt_pk_bf16_f32 v148, v64, v65
	v_cvt_pk_bf16_f32 v149, v66, v67
	s_waitcnt lgkmcnt(0)
	v_mfma_f32_32x32x16_bf16 v[80:95], v[160:163], v[140:143], v[80:95]
	ds_read_b64_tr_b16 v[64:65], v188 offset:63488
	ds_read_b64_tr_b16 v[66:67], v188 offset:64000
	ds_read_b128 v[140:143], v168 offset:2048
	v_add_f32_e32 v144, v70, v144
	v_add_f32_e32 v144, v71, v144
	v_add_f32_e32 v144, v72, v144
	v_add_f32_e32 v144, v73, v144
	v_cvt_pk_bf16_f32 v150, v68, v69
	v_cvt_pk_bf16_f32 v151, v70, v71
	s_waitcnt lgkmcnt(0)
	v_mfma_f32_32x32x16_bf16 v[96:111], v[132:135], v[140:143], v[96:111]
	ds_read_b64_tr_b16 v[68:69], v188 offset:60416
	ds_read_b64_tr_b16 v[70:71], v188 offset:60928
	ds_read_b128 v[132:135], v168 offset:3072
	v_add_f32_e32 v140, v74, v144
	v_add_f32_e32 v140, v75, v140
	v_add_f32_e32 v140, v76, v140
	v_add_f32_e32 v140, v77, v140
	v_cvt_pk_bf16_f32 v144, v72, v73
	v_cvt_pk_bf16_f32 v145, v74, v75
	s_waitcnt lgkmcnt(0)
	v_mfma_f32_32x32x16_bf16 v[80:95], v[136:139], v[132:135], v[80:95]
	ds_read_b64_tr_b16 v[72:73], v188 offset:64512
	ds_read_b64_tr_b16 v[74:75], v188 offset:65024
	ds_read_b128 v[132:135], v168 offset:3072
	v_add_f32_e32 v136, v78, v140
	v_add_f32_e32 v136, v79, v136
	v_add_f32_e32 v136, 0, v136
	v_cvt_pk_bf16_f32 v146, v76, v77
	v_cvt_pk_bf16_f32 v147, v78, v79
	s_waitcnt lgkmcnt(0)
	v_mfma_f32_32x32x16_bf16 v[96:111], v[128:131], v[132:135], v[96:111]
	v_mfma_f32_32x32x16_bf16 v[48:63], v[156:159], v[170:173], v[48:63]
	ds_read_b64_tr_b16 v[76:77], v177 offset:40960
	ds_read_b64_tr_b16 v[78:79], v177 offset:41472
	v_exp_f32_e32 v80, v80
	v_exp_f32_e32 v81, v81
	v_mfma_f32_32x32x16_bf16 v[32:47], v[156:159], v[112:115], v[32:47]
	ds_read_b64_tr_b16 v[128:129], v177 offset:45056
	ds_read_b64_tr_b16 v[130:131], v177 offset:45568
	v_exp_f32_e32 v82, v82
	v_exp_f32_e32 v83, v83
	v_mfma_f32_32x32x16_bf16 v[48:63], v[152:155], v[116:119], v[48:63]
	ds_read_b64_tr_b16 v[112:113], v177 offset:41984
	ds_read_b64_tr_b16 v[114:115], v177 offset:42496
	v_exp_f32_e32 v84, v84
	v_exp_f32_e32 v85, v85
	v_mfma_f32_32x32x16_bf16 v[32:47], v[152:155], v[120:123], v[32:47]
	ds_read_b64_tr_b16 v[116:117], v177 offset:46080
	ds_read_b64_tr_b16 v[118:119], v177 offset:46592
	v_exp_f32_e32 v86, v86
	v_exp_f32_e32 v87, v87
	v_mfma_f32_32x32x16_bf16 v[48:63], v[148:151], v[124:127], v[48:63]
	ds_read_b64_tr_b16 v[120:121], v177 offset:43008
	ds_read_b64_tr_b16 v[122:123], v177 offset:43520
	v_exp_f32_e32 v88, v88
	v_exp_f32_e32 v89, v89
	v_mfma_f32_32x32x16_bf16 v[32:47], v[148:151], v[64:67], v[32:47]
	ds_read_b64_tr_b16 v[124:125], v177 offset:47104
	ds_read_b64_tr_b16 v[126:127], v177 offset:47616
	v_exp_f32_e32 v90, v90
	v_exp_f32_e32 v91, v91
	v_mfma_f32_32x32x16_bf16 v[48:63], v[144:147], v[68:71], v[48:63]
	ds_read_b64_tr_b16 v[64:65], v177 offset:44032
	ds_read_b64_tr_b16 v[66:67], v177 offset:44544
	v_exp_f32_e32 v92, v92
	v_exp_f32_e32 v93, v93
	v_mfma_f32_32x32x16_bf16 v[32:47], v[144:147], v[72:75], v[32:47]
	ds_read_b64_tr_b16 v[68:69], v177 offset:48128
	ds_read_b64_tr_b16 v[70:71], v177 offset:48640
	v_exp_f32_e32 v94, v94
	v_exp_f32_e32 v95, v95
	s_waitcnt lgkmcnt(14)
	v_mfma_f32_32x32x16_bf16 v[16:31], v[156:159], v[76:79], v[16:31]
	v_exp_f32_e32 v96, v96
	v_exp_f32_e32 v97, v97
	s_waitcnt lgkmcnt(12)
; #define SBAR() __builtin_amdgcn_sched_barrier(0)
;   #define RESC() do{ if(!NOMAX&&resc){ asm volatile("s_waitcnt lgkmcnt(0)":::"memory"); \
;       _Pragma("unroll") for(int d_=0;d_<2*VM;++d_) _Pragma("unroll") for(int r=0;r<16;++r)o[d_][r]*=wsf[crow(r,hi)]; } }while(0)
;   #define PKW(P,B) cvtpk_s(P[B],P[B+1])
; __device__ __forceinline__ void pv(f32x16*o,int vb,bf16x8 pa0,bf16x8 pa1,bf16x8 pa2,bf16x8 pa3){
;   #pragma unroll
;   for(int d0=0;d0<2;++d0){s16x4 lo[4],hi[4];
;     #pragma unroll
;     for(int ks=0;ks<4;++ks){
;       asm volatile("ds_read_b64_tr_b16 %0,%1 offset:%c2":"=&v"(lo[ks]):"v"(vb),"i"(d0*4096+ks*1024):"memory");
;       asm volatile("ds_read_b64_tr_b16 %0,%1 offset:%c2":"=&v"(hi[ks]):"v"(vb),"i"(d0*4096+ks*1024+512):"memory");}
;     asm volatile("s_waitcnt lgkmcnt(0)":::"memory");SBAR();
;     ...
;     o[d0]=__builtin_amdgcn_mfma_f32_32x32x16_bf16(pa0,PK(0),o[d0],0,0,0);
;     o[d0]=__builtin_amdgcn_mfma_f32_32x32x16_bf16(pa1,PK(1),o[d0],0,0,0);
;     o[d0]=__builtin_amdgcn_mfma_f32_32x32x16_bf16(pa2,PK(2),o[d0],0,0,0);
;     o[d0]=__builtin_amdgcn_mfma_f32_32x32x16_bf16(pa3,PK(3),o[d0],0,0,0);
;     ...
;   }
; }
; template<int THRL,int VM,bool NOMAX> __device__ __forceinline__ void attn_unit(const bf16*Qb,const bf16*__restrict__ Kh,const bf16*__restrict__ Vh,bf16*Ob,const int NT,const int sp,float*wscr,char*shm){
;     ...
;   STEP(pB0,pB1,pA0,pA1,NT-1,false,false,false); RESC();
;   { float sacc=pB0[0]+pB0[1]; _Pragma("unroll") for(int r=2;r<16;++r)sacc+=pB0[r]; _Pragma("unroll") for(int r=0;r<16;++r)sacc+=pB1[r]; l_reg+=sacc;
;     pw0=(u32x4){PKW(pB0,0),PKW(pB0,2),PKW(pB0,4),PKW(pB0,6)};pw1=(u32x4){PKW(pB0,8),PKW(pB0,10),PKW(pB0,12),PKW(pB0,14)};pw2=(u32x4){PKW(pB1,0),PKW(pB1,2),PKW(pB1,4),PKW(pB1,6)};pw3=(u32x4){PKW(pB1,8),PKW(pB1,10),PKW(pB1,12),PKW(pB1,14)};
;     SBAR(); pv(o,vb0+VM*sl_cur,PAF(0),PAF(1),PAF(2),PAF(3)); if constexpr(VM==2) pv(o+2,vb0+VM*sl_cur+8192,PAF(0),PAF(1),PAF(2),PAF(3)); }
;     ...
;   {auto rr=__builtin_amdgcn_permlane32_swap(__float_as_uint(l_reg),__float_as_uint(l_reg),false,false);l_reg=__uint_as_float(rr[0])+__uint_as_float(rr[1]);}
;   if(hi==0)wsf[32+r32]=l_reg;asm volatile("s_waitcnt lgkmcnt(0)":::"memory");
	v_mfma_f32_32x32x16_bf16 v[0:15], v[156:159], v[128:131], v[0:15]
	v_exp_f32_e32 v98, v98
	v_exp_f32_e32 v99, v99
	s_waitcnt lgkmcnt(10)
	v_mfma_f32_32x32x16_bf16 v[16:31], v[152:155], v[112:115], v[16:31]
	v_exp_f32_e32 v100, v100
	v_exp_f32_e32 v101, v101
	s_waitcnt lgkmcnt(8)
	v_mfma_f32_32x32x16_bf16 v[0:15], v[152:155], v[116:119], v[0:15]
	v_exp_f32_e32 v102, v102
	v_exp_f32_e32 v103, v103
	s_waitcnt lgkmcnt(6)
	v_mfma_f32_32x32x16_bf16 v[16:31], v[148:151], v[120:123], v[16:31]
	v_exp_f32_e32 v104, v104
	v_exp_f32_e32 v105, v105
	s_waitcnt lgkmcnt(4)
	v_mfma_f32_32x32x16_bf16 v[0:15], v[148:151], v[124:127], v[0:15]
	v_exp_f32_e32 v106, v106
	v_exp_f32_e32 v107, v107
	s_waitcnt lgkmcnt(2)
	v_mfma_f32_32x32x16_bf16 v[16:31], v[144:147], v[64:67], v[16:31]
	v_exp_f32_e32 v108, v108
	v_exp_f32_e32 v109, v109
	s_waitcnt lgkmcnt(0)
	v_mfma_f32_32x32x16_bf16 v[0:15], v[144:147], v[68:71], v[0:15]
	v_exp_f32_e32 v110, v110
	v_exp_f32_e32 v111, v111
	v_add_f32_e32 v64, v80, v81
	v_add_f32_e32 v64, v82, v64
	v_add_f32_e32 v64, v83, v64
	v_add_f32_e32 v64, v84, v64
	v_add_f32_e32 v64, v85, v64
	v_add_f32_e32 v64, v86, v64
	v_add_f32_e32 v64, v87, v64
	v_add_f32_e32 v64, v88, v64
	v_add_f32_e32 v64, v89, v64
	v_add_f32_e32 v64, v90, v64
	v_add_f32_e32 v64, v91, v64
	v_add_f32_e32 v64, v92, v64
	v_add_f32_e32 v64, v93, v64
	v_add_f32_e32 v64, v94, v64
	v_add_f32_e32 v64, v95, v64
	v_add_f32_e32 v64, v64, v96
	v_add_f32_e32 v64, v97, v64
	v_add_f32_e32 v64, v98, v64
	v_add_f32_e32 v64, v99, v64
	v_add_f32_e32 v64, v100, v64
	v_add_f32_e32 v64, v101, v64
	v_add_f32_e32 v64, v102, v64
	v_add_f32_e32 v64, v103, v64
	v_add_f32_e32 v64, v104, v64
	v_add_f32_e32 v64, v105, v64
	v_add_f32_e32 v64, v106, v64
	v_add_f32_e32 v64, v107, v64
	v_add_f32_e32 v64, v108, v64
	v_add_f32_e32 v64, v109, v64
	v_add_f32_e32 v64, v110, v64
	v_add_f32_e32 v64, v111, v64
	v_add_f32_e32 v65, v174, v136
	v_add_f32_e32 v64, v65, v64
	v_cvt_pk_bf16_f32 v66, v80, v81
	v_cvt_pk_bf16_f32 v67, v82, v83
	v_cvt_pk_bf16_f32 v68, v84, v85
	v_cvt_pk_bf16_f32 v69, v86, v87
	v_cvt_pk_bf16_f32 v70, v88, v89
	v_cvt_pk_bf16_f32 v71, v90, v91
	v_cvt_pk_bf16_f32 v72, v92, v93
	v_cvt_pk_bf16_f32 v73, v94, v95
	v_cvt_pk_bf16_f32 v74, v96, v97
	v_cvt_pk_bf16_f32 v75, v98, v99
	v_cvt_pk_bf16_f32 v76, v100, v101
	v_cvt_pk_bf16_f32 v77, v102, v103
	v_cvt_pk_bf16_f32 v78, v104, v105
	v_cvt_pk_bf16_f32 v79, v106, v107
	v_cvt_pk_bf16_f32 v80, v108, v109
	v_cvt_pk_bf16_f32 v81, v110, v111
	ds_read_b64_tr_b16 v[82:83],v176 offset:0
	ds_read_b64_tr_b16 v[84:85],v176 offset:512
	ds_read_b64_tr_b16 v[86:87],v176 offset:1024
	ds_read_b64_tr_b16 v[88:89],v176 offset:1536
	ds_read_b64_tr_b16 v[90:91],v176 offset:2048
	ds_read_b64_tr_b16 v[92:93],v176 offset:2560
	ds_read_b64_tr_b16 v[94:95],v176 offset:3072
	ds_read_b64_tr_b16 v[96:97],v176 offset:3584
	s_waitcnt lgkmcnt(0)
	s_nop 0
	v_mfma_f32_32x32x16_bf16 v[48:63], v[66:69], v[82:85], v[48:63]
	ds_read_b64_tr_b16 v[82:83],v176 offset:4096
	ds_read_b64_tr_b16 v[84:85],v176 offset:4608
	v_mfma_f32_32x32x16_bf16 v[48:63], v[70:73], v[86:89], v[48:63]
	ds_read_b64_tr_b16 v[86:87],v176 offset:5120
	ds_read_b64_tr_b16 v[88:89],v176 offset:5632
	v_mfma_f32_32x32x16_bf16 v[48:63], v[74:77], v[90:93], v[48:63]
	ds_read_b64_tr_b16 v[90:91],v176 offset:6144
	ds_read_b64_tr_b16 v[92:93],v176 offset:6656
	ds_read_b64_tr_b16 v[98:99],v176 offset:7168
	ds_read_b64_tr_b16 v[100:101],v176 offset:7680
	s_waitcnt lgkmcnt(0)
	v_mfma_f32_32x32x16_bf16 v[48:63], v[78:81], v[94:97], v[48:63]
	v_mfma_f32_32x32x16_bf16 v[32:47], v[66:69], v[82:85], v[32:47]
	v_add_u32_e32 v65, 0x2000, v176
	ds_read_b64_tr_b16 v[82:83],v65 offset:0
	ds_read_b64_tr_b16 v[84:85],v65 offset:512
	v_mfma_f32_32x32x16_bf16 v[32:47], v[70:73], v[86:89], v[32:47]
	ds_read_b64_tr_b16 v[86:87],v65 offset:1024
	ds_read_b64_tr_b16 v[88:89],v65 offset:1536
	v_mfma_f32_32x32x16_bf16 v[32:47], v[74:77], v[90:93], v[32:47]
	ds_read_b64_tr_b16 v[90:91],v65 offset:2048
	ds_read_b64_tr_b16 v[92:93],v65 offset:2560
	ds_read_b64_tr_b16 v[94:95],v65 offset:3072
	ds_read_b64_tr_b16 v[96:97],v65 offset:3584
	s_waitcnt lgkmcnt(0)
	v_mfma_f32_32x32x16_bf16 v[32:47], v[78:81], v[98:101], v[32:47]
	v_mfma_f32_32x32x16_bf16 v[16:31], v[66:69], v[82:85], v[16:31]
	ds_read_b64_tr_b16 v[82:83],v65 offset:4096
	ds_read_b64_tr_b16 v[84:85],v65 offset:4608
	v_mfma_f32_32x32x16_bf16 v[16:31], v[70:73], v[86:89], v[16:31]
	ds_read_b64_tr_b16 v[86:87],v65 offset:5120
	ds_read_b64_tr_b16 v[88:89],v65 offset:5632
	v_mfma_f32_32x32x16_bf16 v[16:31], v[74:77], v[90:93], v[16:31]
	ds_read_b64_tr_b16 v[90:91],v65 offset:6144
	ds_read_b64_tr_b16 v[92:93],v65 offset:6656
	ds_read_b64_tr_b16 v[98:99],v65 offset:7168
	ds_read_b64_tr_b16 v[100:101],v65 offset:7680
	s_waitcnt lgkmcnt(0)
	v_mfma_f32_32x32x16_bf16 v[16:31], v[78:81], v[94:97], v[16:31]
	v_mfma_f32_32x32x16_bf16 v[0:15], v[66:69], v[82:85], v[0:15]
	v_mov_b32_e32 v65, v64
	s_nop 1
	v_permlane32_swap_b32_e32 v64, v65
	v_cmp_gt_u32_e32 vcc, 32, v187
	v_mfma_f32_32x32x16_bf16 v[0:15], v[70:73], v[86:89], v[0:15]
	v_mfma_f32_32x32x16_bf16 v[0:15], v[74:77], v[90:93], v[0:15]
	v_mfma_f32_32x32x16_bf16 v[0:15], v[78:81], v[98:101], v[0:15]
	s_and_saveexec_b64 s[16:17], vcc
	s_cbranch_execz .LBB0_870
	v_add_f32_e32 v64, v64, v65
	v_lshl_add_u32 v65, v186, 2, s34
	ds_write_b32 v65, v64 offset:128
	s_branch .LBB0_870
